# GEMM loops: 4 segments of 32 MFMAs (8 barriers/iteration) plus the A-fragment LDS address adds hoisted out of the loop
# speedup vs baseline: 1.0112x; 1.0112x over previous
.LBB0_37:
	s_add_i32 s69, s48, 2
	s_add_u32 s46, s0, 0x100
	s_addc_u32 s47, s1, 0
	s_add_i32 s70, 0, 0x10000
	ds_read_b128 v[140:143], v153
	ds_read_b128 v[144:147], v153 offset:1024
	ds_read_b128 v[148:151], v153 offset:2048
	ds_read_b128 v[168:171], v153 offset:3072
	s_cmp_eq_u32 s12, s48
	s_cselect_b32 s48, s44, s13
	s_cselect_b32 s51, s43, s47
	s_cselect_b32 s50, s42, s46
	s_cselect_b32 s49, s45, s68
	v_lshl_add_u64 v[156:157], s[0:1], 0, v[136:137]
	ds_read_b128 v[172:175], v155
	ds_read_b128 v[176:179], v155 offset:1024
	ds_read_b128 v[180:183], v155 offset:2048
	ds_read_b128 v[184:187], v155 offset:3072
	ds_read_b128 v[188:191], v155 offset:4096
	ds_read_b128 v[192:195], v155 offset:5120
	ds_read_b128 v[196:199], v155 offset:6144
	ds_read_b128 v[224:227], v155 offset:7168
	s_add_i32 m0, s53, 0xc000
	s_nop 0
	global_load_lds_dwordx4 v[156:157], off
	v_lshl_add_u64 v[156:157], s[0:1], 0, v[138:139]
	s_add_i32 m0, s53, 0xe000
	s_nop 0
	global_load_lds_dwordx4 v[156:157], off
	s_add_i32 s71, 0, 0x14000
	s_add_i32 s0, s70, s52
	ds_read_b128 v[228:231], v153 offset:16384
	ds_read_b128 v[232:235], v153 offset:17408
	ds_read_b128 v[236:239], v153 offset:18432
	ds_read_b128 v[240:243], v153 offset:19456
	s_waitcnt lgkmcnt(0)
	s_barrier
	v_mfma_f32_16x16x32_bf16 v[126:129], v[140:143], v[172:175], v[126:129]
	v_mfma_f32_16x16x32_bf16 v[122:125], v[148:151], v[172:175], v[122:125]
	v_mfma_f32_16x16x32_bf16 v[110:113], v[140:143], v[180:183], v[110:113]
	v_mfma_f32_16x16x32_bf16 v[106:109], v[148:151], v[180:183], v[106:109]
	v_mfma_f32_16x16x32_bf16 v[94:97], v[140:143], v[188:191], v[94:97]
	v_mfma_f32_16x16x32_bf16 v[90:93], v[148:151], v[188:191], v[90:93]
	v_mfma_f32_16x16x32_bf16 v[78:81], v[140:143], v[196:199], v[78:81]
	v_mfma_f32_16x16x32_bf16 v[74:77], v[148:151], v[196:199], v[74:77]
	v_mfma_f32_16x16x32_bf16 v[126:129], v[144:147], v[176:179], v[126:129]
	v_mfma_f32_16x16x32_bf16 v[122:125], v[168:171], v[176:179], v[122:125]
	v_mfma_f32_16x16x32_bf16 v[110:113], v[144:147], v[184:187], v[110:113]
	v_mfma_f32_16x16x32_bf16 v[106:109], v[168:171], v[184:187], v[106:109]
	v_mfma_f32_16x16x32_bf16 v[94:97], v[144:147], v[192:195], v[94:97]
	v_mfma_f32_16x16x32_bf16 v[90:93], v[168:171], v[192:195], v[90:93]
	v_mfma_f32_16x16x32_bf16 v[78:81], v[144:147], v[224:227], v[78:81]
	v_mfma_f32_16x16x32_bf16 v[74:77], v[168:171], v[224:227], v[74:77]
	v_mfma_f32_16x16x32_bf16 v[118:121], v[228:231], v[172:175], v[118:121]
	v_mfma_f32_16x16x32_bf16 v[114:117], v[236:239], v[172:175], v[114:117]
	v_mfma_f32_16x16x32_bf16 v[102:105], v[228:231], v[180:183], v[102:105]
	v_mfma_f32_16x16x32_bf16 v[98:101], v[236:239], v[180:183], v[98:101]
	v_mfma_f32_16x16x32_bf16 v[86:89], v[228:231], v[188:191], v[86:89]
	v_mfma_f32_16x16x32_bf16 v[82:85], v[236:239], v[188:191], v[82:85]
	v_mfma_f32_16x16x32_bf16 v[70:73], v[228:231], v[196:199], v[70:73]
	v_mfma_f32_16x16x32_bf16 v[66:69], v[236:239], v[196:199], v[66:69]
	v_mfma_f32_16x16x32_bf16 v[118:121], v[232:235], v[176:179], v[118:121]
	v_mfma_f32_16x16x32_bf16 v[114:117], v[240:243], v[176:179], v[114:117]
	v_mfma_f32_16x16x32_bf16 v[102:105], v[232:235], v[184:187], v[102:105]
	v_mfma_f32_16x16x32_bf16 v[98:101], v[240:243], v[184:187], v[98:101]
	v_mfma_f32_16x16x32_bf16 v[86:89], v[232:235], v[192:195], v[86:89]
	v_mfma_f32_16x16x32_bf16 v[82:85], v[240:243], v[192:195], v[82:85]
	v_mfma_f32_16x16x32_bf16 v[70:73], v[232:235], v[224:227], v[70:73]
	v_mfma_f32_16x16x32_bf16 v[66:69], v[240:243], v[224:227], v[66:69]
	s_barrier
	s_mov_b32 m0, s53
	s_add_u32 s78, s50, s94
	s_addc_u32 s79, s51, s95
	ds_read_b128 v[172:175], v155 offset:16384
	ds_read_b128 v[176:179], v155 offset:17408
	ds_read_b128 v[180:183], v155 offset:18432
	ds_read_b128 v[184:187], v155 offset:19456
	ds_read_b128 v[188:191], v155 offset:20480
	ds_read_b128 v[192:195], v155 offset:21504
	ds_read_b128 v[196:199], v155 offset:22528
	ds_read_b128 v[224:227], v155 offset:23552
	global_load_lds_dwordx4 v134, s[50:51]
	s_mov_b32 m0, s54
	s_nop 0
	global_load_lds_dwordx4 v132, s[50:51]
	s_add_u32 s76, s48, s94
	s_addc_u32 s77, s49, s95
	s_mov_b32 m0, s0
	s_nop 0
	global_load_lds_dwordx4 v0, s[48:49]
	s_add_i32 m0, s0, 0x2000
	s_nop 0
	global_load_lds_dwordx4 v130, s[48:49]
	s_add_u32 s0, s48, 0x160000
	s_addc_u32 s1, s49, 0
	s_add_i32 s70, s71, s52
	s_mov_b32 m0, s70
	s_nop 0
	global_load_lds_dwordx4 v0, s[0:1]
	s_add_i32 m0, s70, 0x2000
	s_nop 0
	global_load_lds_dwordx4 v130, s[0:1]
	s_waitcnt vmcnt(6) lgkmcnt(0)
	s_barrier
	v_mfma_f32_16x16x32_bf16 v[62:65], v[140:143], v[172:175], v[62:65]
	v_mfma_f32_16x16x32_bf16 v[58:61], v[148:151], v[172:175], v[58:61]
	v_mfma_f32_16x16x32_bf16 v[46:49], v[140:143], v[180:183], v[46:49]
	v_mfma_f32_16x16x32_bf16 v[42:45], v[148:151], v[180:183], v[42:45]
	v_mfma_f32_16x16x32_bf16 v[30:33], v[140:143], v[188:191], v[30:33]
	v_mfma_f32_16x16x32_bf16 v[26:29], v[148:151], v[188:191], v[26:29]
	v_mfma_f32_16x16x32_bf16 v[14:17], v[140:143], v[196:199], v[14:17]
	v_mfma_f32_16x16x32_bf16 v[10:13], v[148:151], v[196:199], v[10:13]
	v_mfma_f32_16x16x32_bf16 v[62:65], v[144:147], v[176:179], v[62:65]
	v_mfma_f32_16x16x32_bf16 v[58:61], v[168:171], v[176:179], v[58:61]
	v_mfma_f32_16x16x32_bf16 v[46:49], v[144:147], v[184:187], v[46:49]
	v_mfma_f32_16x16x32_bf16 v[42:45], v[168:171], v[184:187], v[42:45]
	v_mfma_f32_16x16x32_bf16 v[30:33], v[144:147], v[192:195], v[30:33]
	v_mfma_f32_16x16x32_bf16 v[26:29], v[168:171], v[192:195], v[26:29]
	v_mfma_f32_16x16x32_bf16 v[14:17], v[144:147], v[224:227], v[14:17]
	v_mfma_f32_16x16x32_bf16 v[10:13], v[168:171], v[224:227], v[10:13]
	v_mfma_f32_16x16x32_bf16 v[54:57], v[228:231], v[172:175], v[54:57]
	v_mfma_f32_16x16x32_bf16 v[50:53], v[236:239], v[172:175], v[50:53]
	v_mfma_f32_16x16x32_bf16 v[38:41], v[228:231], v[180:183], v[38:41]
	v_mfma_f32_16x16x32_bf16 v[34:37], v[236:239], v[180:183], v[34:37]
	v_mfma_f32_16x16x32_bf16 v[22:25], v[228:231], v[188:191], v[22:25]
	v_mfma_f32_16x16x32_bf16 v[18:21], v[236:239], v[188:191], v[18:21]
	v_mfma_f32_16x16x32_bf16 v[6:9], v[228:231], v[196:199], v[6:9]
	v_mfma_f32_16x16x32_bf16 v[2:5], v[236:239], v[196:199], v[2:5]
	v_mfma_f32_16x16x32_bf16 v[54:57], v[232:235], v[176:179], v[54:57]
	v_mfma_f32_16x16x32_bf16 v[50:53], v[240:243], v[176:179], v[50:53]
	v_mfma_f32_16x16x32_bf16 v[38:41], v[232:235], v[184:187], v[38:41]
	v_mfma_f32_16x16x32_bf16 v[34:37], v[240:243], v[184:187], v[34:37]
	v_mfma_f32_16x16x32_bf16 v[22:25], v[232:235], v[192:195], v[22:25]
	v_mfma_f32_16x16x32_bf16 v[18:21], v[240:243], v[192:195], v[18:21]
	v_mfma_f32_16x16x32_bf16 v[6:9], v[232:235], v[224:227], v[6:9]
	v_mfma_f32_16x16x32_bf16 v[2:5], v[240:243], v[224:227], v[2:5]
	s_barrier
	s_add_i32 s70, 0, 0x18000
	ds_read_b128 v[140:143], v153 offset:32768
	ds_read_b128 v[144:147], v153 offset:33792
	ds_read_b128 v[148:151], v153 offset:34816
	ds_read_b128 v[168:171], v153 offset:35840
	s_add_u32 s0, s50, 0x2c0000
	s_addc_u32 s1, s51, 0
	ds_read_b128 v[172:175], v155 offset:32768
	ds_read_b128 v[176:179], v155 offset:33792
	ds_read_b128 v[180:183], v155 offset:34816
	ds_read_b128 v[184:187], v155 offset:35840
	ds_read_b128 v[188:191], v155 offset:36864
	ds_read_b128 v[192:195], v155 offset:37888
	ds_read_b128 v[196:199], v155 offset:38912
	ds_read_b128 v[224:227], v155 offset:39936
	s_mov_b32 m0, s55
	s_nop 0
	global_load_lds_dwordx4 v134, s[0:1]
	s_mov_b32 m0, s56
	s_nop 0
	global_load_lds_dwordx4 v132, s[0:1]
	s_add_i32 s50, 0, 0x1c000
	s_add_i32 s0, s70, s52
	ds_read_b128 v[228:231], v153 offset:49152
	ds_read_b128 v[232:235], v153 offset:50176
	ds_read_b128 v[236:239], v153 offset:51200
	ds_read_b128 v[240:243], v153 offset:52224
	s_waitcnt lgkmcnt(0)
	s_barrier
	v_mfma_f32_16x16x32_bf16 v[126:129], v[140:143], v[172:175], v[126:129]
	v_mfma_f32_16x16x32_bf16 v[122:125], v[148:151], v[172:175], v[122:125]
	v_mfma_f32_16x16x32_bf16 v[110:113], v[140:143], v[180:183], v[110:113]
	v_mfma_f32_16x16x32_bf16 v[106:109], v[148:151], v[180:183], v[106:109]
	v_mfma_f32_16x16x32_bf16 v[94:97], v[140:143], v[188:191], v[94:97]
	v_mfma_f32_16x16x32_bf16 v[90:93], v[148:151], v[188:191], v[90:93]
	v_mfma_f32_16x16x32_bf16 v[78:81], v[140:143], v[196:199], v[78:81]
	v_mfma_f32_16x16x32_bf16 v[74:77], v[148:151], v[196:199], v[74:77]
	v_mfma_f32_16x16x32_bf16 v[126:129], v[144:147], v[176:179], v[126:129]
	v_mfma_f32_16x16x32_bf16 v[122:125], v[168:171], v[176:179], v[122:125]
	v_mfma_f32_16x16x32_bf16 v[110:113], v[144:147], v[184:187], v[110:113]
	v_mfma_f32_16x16x32_bf16 v[106:109], v[168:171], v[184:187], v[106:109]
	v_mfma_f32_16x16x32_bf16 v[94:97], v[144:147], v[192:195], v[94:97]
	v_mfma_f32_16x16x32_bf16 v[90:93], v[168:171], v[192:195], v[90:93]
	v_mfma_f32_16x16x32_bf16 v[78:81], v[144:147], v[224:227], v[78:81]
	v_mfma_f32_16x16x32_bf16 v[74:77], v[168:171], v[224:227], v[74:77]
	v_mfma_f32_16x16x32_bf16 v[118:121], v[228:231], v[172:175], v[118:121]
	v_mfma_f32_16x16x32_bf16 v[114:117], v[236:239], v[172:175], v[114:117]
	v_mfma_f32_16x16x32_bf16 v[102:105], v[228:231], v[180:183], v[102:105]
	v_mfma_f32_16x16x32_bf16 v[98:101], v[236:239], v[180:183], v[98:101]
	v_mfma_f32_16x16x32_bf16 v[86:89], v[228:231], v[188:191], v[86:89]
	v_mfma_f32_16x16x32_bf16 v[82:85], v[236:239], v[188:191], v[82:85]
	v_mfma_f32_16x16x32_bf16 v[70:73], v[228:231], v[196:199], v[70:73]
	v_mfma_f32_16x16x32_bf16 v[66:69], v[236:239], v[196:199], v[66:69]
	v_mfma_f32_16x16x32_bf16 v[118:121], v[232:235], v[176:179], v[118:121]
	v_mfma_f32_16x16x32_bf16 v[114:117], v[240:243], v[176:179], v[114:117]
	v_mfma_f32_16x16x32_bf16 v[102:105], v[232:235], v[184:187], v[102:105]
	v_mfma_f32_16x16x32_bf16 v[98:101], v[240:243], v[184:187], v[98:101]
	v_mfma_f32_16x16x32_bf16 v[86:89], v[232:235], v[192:195], v[86:89]
	v_mfma_f32_16x16x32_bf16 v[82:85], v[240:243], v[192:195], v[82:85]
	v_mfma_f32_16x16x32_bf16 v[70:73], v[232:235], v[224:227], v[70:73]
	v_mfma_f32_16x16x32_bf16 v[66:69], v[240:243], v[224:227], v[66:69]
	s_barrier
	s_mov_b32 m0, s57
	ds_read_b128 v[172:175], v155 offset:49152
	ds_read_b128 v[176:179], v155 offset:50176
	ds_read_b128 v[180:183], v155 offset:51200
	ds_read_b128 v[184:187], v155 offset:52224
	ds_read_b128 v[188:191], v155 offset:53248
	ds_read_b128 v[192:195], v155 offset:54272
	ds_read_b128 v[196:199], v155 offset:55296
	ds_read_b128 v[224:227], v155 offset:56320
	global_load_lds_dwordx4 v134, s[78:79]
	s_mov_b32 m0, s58
	s_nop 0
	global_load_lds_dwordx4 v132, s[78:79]
	s_mov_b32 m0, s0
	s_nop 0
	global_load_lds_dwordx4 v0, s[76:77]
	s_add_i32 m0, s0, 0x2000
	s_nop 0
	global_load_lds_dwordx4 v130, s[76:77]
	s_add_u32 s0, s48, 0x160080
	s_addc_u32 s1, s49, 0
	s_add_i32 s48, s50, s52
	s_mov_b32 m0, s48
	s_nop 0
	global_load_lds_dwordx4 v0, s[0:1]
	s_add_i32 m0, s48, 0x2000
	s_nop 0
	global_load_lds_dwordx4 v130, s[0:1]
	s_waitcnt vmcnt(6) lgkmcnt(0)
	s_barrier
	v_mfma_f32_16x16x32_bf16 v[62:65], v[140:143], v[172:175], v[62:65]
	v_mfma_f32_16x16x32_bf16 v[58:61], v[148:151], v[172:175], v[58:61]
	v_mfma_f32_16x16x32_bf16 v[46:49], v[140:143], v[180:183], v[46:49]
	v_mfma_f32_16x16x32_bf16 v[42:45], v[148:151], v[180:183], v[42:45]
	v_mfma_f32_16x16x32_bf16 v[30:33], v[140:143], v[188:191], v[30:33]
	v_mfma_f32_16x16x32_bf16 v[26:29], v[148:151], v[188:191], v[26:29]
	v_mfma_f32_16x16x32_bf16 v[14:17], v[140:143], v[196:199], v[14:17]
	v_mfma_f32_16x16x32_bf16 v[10:13], v[148:151], v[196:199], v[10:13]
	v_mfma_f32_16x16x32_bf16 v[62:65], v[144:147], v[176:179], v[62:65]
	v_mfma_f32_16x16x32_bf16 v[58:61], v[168:171], v[176:179], v[58:61]
	v_mfma_f32_16x16x32_bf16 v[46:49], v[144:147], v[184:187], v[46:49]
	v_mfma_f32_16x16x32_bf16 v[42:45], v[168:171], v[184:187], v[42:45]
	v_mfma_f32_16x16x32_bf16 v[30:33], v[144:147], v[192:195], v[30:33]
	v_mfma_f32_16x16x32_bf16 v[26:29], v[168:171], v[192:195], v[26:29]
	v_mfma_f32_16x16x32_bf16 v[14:17], v[144:147], v[224:227], v[14:17]
	v_mfma_f32_16x16x32_bf16 v[10:13], v[168:171], v[224:227], v[10:13]
	v_mfma_f32_16x16x32_bf16 v[54:57], v[228:231], v[172:175], v[54:57]
	v_mfma_f32_16x16x32_bf16 v[50:53], v[236:239], v[172:175], v[50:53]
	v_mfma_f32_16x16x32_bf16 v[38:41], v[228:231], v[180:183], v[38:41]
	v_mfma_f32_16x16x32_bf16 v[34:37], v[236:239], v[180:183], v[34:37]
	v_mfma_f32_16x16x32_bf16 v[22:25], v[228:231], v[188:191], v[22:25]
	v_mfma_f32_16x16x32_bf16 v[18:21], v[236:239], v[188:191], v[18:21]
	v_mfma_f32_16x16x32_bf16 v[6:9], v[228:231], v[196:199], v[6:9]
	v_mfma_f32_16x16x32_bf16 v[2:5], v[236:239], v[196:199], v[2:5]
	v_mfma_f32_16x16x32_bf16 v[54:57], v[232:235], v[176:179], v[54:57]
	v_mfma_f32_16x16x32_bf16 v[50:53], v[240:243], v[176:179], v[50:53]
	v_mfma_f32_16x16x32_bf16 v[38:41], v[232:235], v[184:187], v[38:41]
	v_mfma_f32_16x16x32_bf16 v[34:37], v[240:243], v[184:187], v[34:37]
	v_mfma_f32_16x16x32_bf16 v[22:25], v[232:235], v[192:195], v[22:25]
	v_mfma_f32_16x16x32_bf16 v[18:21], v[240:243], v[192:195], v[18:21]
	v_mfma_f32_16x16x32_bf16 v[6:9], v[232:235], v[224:227], v[6:9]
	v_mfma_f32_16x16x32_bf16 v[2:5], v[240:243], v[224:227], v[2:5]
	s_barrier
	s_add_u32 s13, s13, 0x100
	s_addc_u32 s68, s68, 0
	s_mov_b64 s[0:1], s[46:47]
	s_mov_b32 s48, s69
	s_cmp_ge_i32 s69, s39
	s_cbranch_scc0 .LBB0_37
	s_cmp_eq_u32 s65, 2
	s_cbranch_scc1 .Lepi10_orig
	v_readlane_b32 s90, v255, 17
	v_readlane_b32 s91, v255, 18
	v_readlane_b32 s96, v255, 19
	v_readlane_b32 s97, v255, 20
	v_lshl_or_b32 v156, s66, 8, v154
	v_lshlrev_b32_e32 v156, 2, v156
	v_lshl_add_u32 v157, v152, 13, v156
	s_lshl_b32 s72, s67, 21
	s_add_u32 s74, s22, s72
	s_addc_u32 s75, s23, 0
	s_add_u32 s76, s22, s72
	s_addc_u32 s77, s23, 0
	s_lshr_b32 s73, s67, 3
	s_mul_i32 s73, s73, 0xc000
	s_add_u32 s73, s73, 0xa000
	s_add_u32 s70, s90, s73
	s_addc_u32 s71, s91, 0
	global_load_dwordx4 v[140:143], v156, s[70:71]
	global_load_dwordx4 v[144:147], v156, s[70:71] offset:64
	global_load_dwordx4 v[148:151], v156, s[70:71] offset:512
	global_load_dwordx4 v[168:171], v156, s[70:71] offset:576
	global_load_dwordx4 v[224:227], v157, s[74:75] nt
	global_load_dwordx4 v[228:231], v157, s[74:75] offset:64 nt
	global_load_dwordx4 v[232:235], v157, s[74:75] offset:512 nt
	global_load_dwordx4 v[236:239], v157, s[74:75] offset:576 nt
	s_add_u32 s74, s74, 0x20000
	s_addc_u32 s75, s75, 0
	global_load_dwordx4 v[240:243], v157, s[74:75] nt
	global_load_dwordx4 v[244:247], v157, s[74:75] offset:64 nt
	s_waitcnt vmcnt(5)
	v_pk_fma_f32 v[128:129], v[128:129], v[142:143], v[226:227]
	v_pk_fma_f32 v[126:127], v[126:127], v[140:141], v[224:225]
	global_store_dwordx4 v157, v[126:129], s[76:77] nt
	global_load_dwordx4 v[224:227], v157, s[74:75] offset:512 nt
	s_waitcnt vmcnt(6)
	v_pk_fma_f32 v[124:125], v[124:125], v[146:147], v[230:231]
	v_pk_fma_f32 v[122:123], v[122:123], v[144:145], v[228:229]
	global_store_dwordx4 v157, v[122:125], s[76:77] offset:64 nt
	global_load_dwordx4 v[228:231], v157, s[74:75] offset:576 nt
	s_waitcnt vmcnt(7)
	v_pk_fma_f32 v[120:121], v[120:121], v[150:151], v[234:235]
	v_pk_fma_f32 v[118:119], v[118:119], v[148:149], v[232:233]
	global_store_dwordx4 v157, v[118:121], s[76:77] offset:512 nt
	s_add_u32 s74, s74, 0x20000
	s_addc_u32 s75, s75, 0
	global_load_dwordx4 v[232:235], v157, s[74:75] nt
	s_waitcnt vmcnt(8)
	v_pk_fma_f32 v[116:117], v[116:117], v[170:171], v[238:239]
	v_pk_fma_f32 v[114:115], v[114:115], v[168:169], v[236:237]
	global_store_dwordx4 v157, v[114:117], s[76:77] offset:576 nt
	global_load_dwordx4 v[236:239], v157, s[74:75] offset:64 nt
	s_add_u32 s76, s76, 0x20000
	s_addc_u32 s77, s77, 0
	s_waitcnt vmcnt(9)
	v_pk_fma_f32 v[112:113], v[112:113], v[142:143], v[242:243]
	v_pk_fma_f32 v[110:111], v[110:111], v[140:141], v[240:241]
	global_store_dwordx4 v157, v[110:113], s[76:77] nt
	global_load_dwordx4 v[240:243], v157, s[74:75] offset:512 nt
	s_waitcnt vmcnt(10)
	v_pk_fma_f32 v[108:109], v[108:109], v[146:147], v[246:247]
	v_pk_fma_f32 v[106:107], v[106:107], v[144:145], v[244:245]
	global_store_dwordx4 v157, v[106:109], s[76:77] offset:64 nt
	global_load_dwordx4 v[244:247], v157, s[74:75] offset:576 nt
	s_waitcnt vmcnt(10)
	v_pk_fma_f32 v[104:105], v[104:105], v[150:151], v[226:227]
	v_pk_fma_f32 v[102:103], v[102:103], v[148:149], v[224:225]
	global_store_dwordx4 v157, v[102:105], s[76:77] offset:512 nt
	s_add_u32 s74, s74, 0x20000
	s_addc_u32 s75, s75, 0
	global_load_dwordx4 v[224:227], v157, s[74:75] nt
	s_waitcnt vmcnt(10)
	v_pk_fma_f32 v[100:101], v[100:101], v[170:171], v[230:231]
	v_pk_fma_f32 v[98:99], v[98:99], v[168:169], v[228:229]
	global_store_dwordx4 v157, v[98:101], s[76:77] offset:576 nt
	global_load_dwordx4 v[228:231], v157, s[74:75] offset:64 nt
	s_add_u32 s76, s76, 0x20000
	s_addc_u32 s77, s77, 0
	s_waitcnt vmcnt(10)
	v_pk_fma_f32 v[96:97], v[96:97], v[142:143], v[234:235]
	v_pk_fma_f32 v[94:95], v[94:95], v[140:141], v[232:233]
	global_store_dwordx4 v157, v[94:97], s[76:77] nt
	global_load_dwordx4 v[232:235], v157, s[74:75] offset:512 nt
	s_waitcnt vmcnt(10)
	v_pk_fma_f32 v[92:93], v[92:93], v[146:147], v[238:239]
	v_pk_fma_f32 v[90:91], v[90:91], v[144:145], v[236:237]
	global_store_dwordx4 v157, v[90:93], s[76:77] offset:64 nt
	global_load_dwordx4 v[236:239], v157, s[74:75] offset:576 nt
	s_waitcnt vmcnt(10)
	v_pk_fma_f32 v[88:89], v[88:89], v[150:151], v[242:243]
	v_pk_fma_f32 v[86:87], v[86:87], v[148:149], v[240:241]
	global_store_dwordx4 v157, v[86:89], s[76:77] offset:512 nt
	s_add_u32 s74, s74, 0xa0000
	s_addc_u32 s75, s75, 0
	global_load_dwordx4 v[240:243], v157, s[74:75] nt
	s_waitcnt vmcnt(10)
	v_pk_fma_f32 v[84:85], v[84:85], v[170:171], v[246:247]
	v_pk_fma_f32 v[82:83], v[82:83], v[168:169], v[244:245]
	global_store_dwordx4 v157, v[82:85], s[76:77] offset:576 nt
	global_load_dwordx4 v[244:247], v157, s[74:75] offset:64 nt
	s_add_u32 s76, s76, 0x20000
	s_addc_u32 s77, s77, 0
	s_waitcnt vmcnt(10)
	v_pk_fma_f32 v[80:81], v[80:81], v[142:143], v[226:227]
	v_pk_fma_f32 v[78:79], v[78:79], v[140:141], v[224:225]
	global_store_dwordx4 v157, v[78:81], s[76:77] nt
	global_load_dwordx4 v[224:227], v157, s[74:75] offset:512 nt
	s_waitcnt vmcnt(10)
	v_pk_fma_f32 v[76:77], v[76:77], v[146:147], v[230:231]
	v_pk_fma_f32 v[74:75], v[74:75], v[144:145], v[228:229]
	global_store_dwordx4 v157, v[74:77], s[76:77] offset:64 nt
	global_load_dwordx4 v[228:231], v157, s[74:75] offset:576 nt
	s_waitcnt vmcnt(10)
	v_pk_fma_f32 v[72:73], v[72:73], v[150:151], v[234:235]
	v_pk_fma_f32 v[70:71], v[70:71], v[148:149], v[232:233]
	global_store_dwordx4 v157, v[70:73], s[76:77] offset:512 nt
	s_add_u32 s74, s74, 0x20000
	s_addc_u32 s75, s75, 0
	global_load_dwordx4 v[232:235], v157, s[74:75] nt
	s_waitcnt vmcnt(10)
	v_pk_fma_f32 v[68:69], v[68:69], v[170:171], v[238:239]
	v_pk_fma_f32 v[66:67], v[66:67], v[168:169], v[236:237]
	global_store_dwordx4 v157, v[66:69], s[76:77] offset:576 nt
	global_load_dwordx4 v[236:239], v157, s[74:75] offset:64 nt
	s_add_u32 s76, s76, 0xa0000
	s_addc_u32 s77, s77, 0
	s_waitcnt vmcnt(10)
	v_pk_fma_f32 v[64:65], v[64:65], v[142:143], v[242:243]
	v_pk_fma_f32 v[62:63], v[62:63], v[140:141], v[240:241]
	global_store_dwordx4 v157, v[62:65], s[76:77] nt
	global_load_dwordx4 v[240:243], v157, s[74:75] offset:512 nt
	s_waitcnt vmcnt(10)
	v_pk_fma_f32 v[60:61], v[60:61], v[146:147], v[246:247]
	v_pk_fma_f32 v[58:59], v[58:59], v[144:145], v[244:245]
	global_store_dwordx4 v157, v[58:61], s[76:77] offset:64 nt
	global_load_dwordx4 v[244:247], v157, s[74:75] offset:576 nt
	s_waitcnt vmcnt(10)
	v_pk_fma_f32 v[56:57], v[56:57], v[150:151], v[226:227]
	v_pk_fma_f32 v[54:55], v[54:55], v[148:149], v[224:225]
	global_store_dwordx4 v157, v[54:57], s[76:77] offset:512 nt
	s_add_u32 s74, s74, 0x20000
	s_addc_u32 s75, s75, 0
	global_load_dwordx4 v[224:227], v157, s[74:75] nt
	s_waitcnt vmcnt(10)
	v_pk_fma_f32 v[52:53], v[52:53], v[170:171], v[230:231]
	v_pk_fma_f32 v[50:51], v[50:51], v[168:169], v[228:229]
	global_store_dwordx4 v157, v[50:53], s[76:77] offset:576 nt
	global_load_dwordx4 v[228:231], v157, s[74:75] offset:64 nt
	s_add_u32 s76, s76, 0x20000
	s_addc_u32 s77, s77, 0
	s_waitcnt vmcnt(10)
	v_pk_fma_f32 v[48:49], v[48:49], v[142:143], v[234:235]
	v_pk_fma_f32 v[46:47], v[46:47], v[140:141], v[232:233]
	global_store_dwordx4 v157, v[46:49], s[76:77] nt
	global_load_dwordx4 v[232:235], v157, s[74:75] offset:512 nt
	s_waitcnt vmcnt(10)
	v_pk_fma_f32 v[44:45], v[44:45], v[146:147], v[238:239]
	v_pk_fma_f32 v[42:43], v[42:43], v[144:145], v[236:237]
	global_store_dwordx4 v157, v[42:45], s[76:77] offset:64 nt
	global_load_dwordx4 v[236:239], v157, s[74:75] offset:576 nt
	s_waitcnt vmcnt(10)
	v_pk_fma_f32 v[40:41], v[40:41], v[150:151], v[242:243]
	v_pk_fma_f32 v[38:39], v[38:39], v[148:149], v[240:241]
	global_store_dwordx4 v157, v[38:41], s[76:77] offset:512 nt
	s_add_u32 s74, s74, 0x20000
	s_addc_u32 s75, s75, 0
	global_load_dwordx4 v[240:243], v157, s[74:75] nt
	s_waitcnt vmcnt(10)
	v_pk_fma_f32 v[36:37], v[36:37], v[170:171], v[246:247]
	v_pk_fma_f32 v[34:35], v[34:35], v[168:169], v[244:245]
	global_store_dwordx4 v157, v[34:37], s[76:77] offset:576 nt
	global_load_dwordx4 v[244:247], v157, s[74:75] offset:64 nt
	s_add_u32 s76, s76, 0x20000
	s_addc_u32 s77, s77, 0
	s_waitcnt vmcnt(10)
	v_pk_fma_f32 v[32:33], v[32:33], v[142:143], v[226:227]
	v_pk_fma_f32 v[30:31], v[30:31], v[140:141], v[224:225]
	global_store_dwordx4 v157, v[30:33], s[76:77] nt
	global_load_dwordx4 v[224:227], v157, s[74:75] offset:512 nt
	s_waitcnt vmcnt(10)
	v_pk_fma_f32 v[28:29], v[28:29], v[146:147], v[230:231]
	v_pk_fma_f32 v[26:27], v[26:27], v[144:145], v[228:229]
	global_store_dwordx4 v157, v[26:29], s[76:77] offset:64 nt
	global_load_dwordx4 v[228:231], v157, s[74:75] offset:576 nt
	s_waitcnt vmcnt(10)
	v_pk_fma_f32 v[24:25], v[24:25], v[150:151], v[234:235]
	v_pk_fma_f32 v[22:23], v[22:23], v[148:149], v[232:233]
	global_store_dwordx4 v157, v[22:25], s[76:77] offset:512 nt
	s_waitcnt vmcnt(9)
	v_pk_fma_f32 v[20:21], v[20:21], v[170:171], v[238:239]
	v_pk_fma_f32 v[18:19], v[18:19], v[168:169], v[236:237]
	global_store_dwordx4 v157, v[18:21], s[76:77] offset:576 nt
	s_add_u32 s76, s76, 0x20000
	s_addc_u32 s77, s77, 0
	s_waitcnt vmcnt(8)
	v_pk_fma_f32 v[16:17], v[16:17], v[142:143], v[242:243]
	v_pk_fma_f32 v[14:15], v[14:15], v[140:141], v[240:241]
	global_store_dwordx4 v157, v[14:17], s[76:77] nt
	s_waitcnt vmcnt(7)
	v_pk_fma_f32 v[12:13], v[12:13], v[146:147], v[246:247]
	v_pk_fma_f32 v[10:11], v[10:11], v[144:145], v[244:245]
	global_store_dwordx4 v157, v[10:13], s[76:77] offset:64 nt
	s_waitcnt vmcnt(6)
	v_pk_fma_f32 v[8:9], v[8:9], v[150:151], v[226:227]
	v_pk_fma_f32 v[6:7], v[6:7], v[148:149], v[224:225]
	global_store_dwordx4 v157, v[6:9], s[76:77] offset:512 nt
	s_waitcnt vmcnt(5)
	v_pk_fma_f32 v[4:5], v[4:5], v[170:171], v[230:231]
	v_pk_fma_f32 v[2:3], v[2:3], v[168:169], v[228:229]
	global_store_dwordx4 v157, v[2:5], s[76:77] offset:576 nt
	s_branch .LBB0_24

.LBB0_234:
	s_add_u32 s39, s46, 0xfff80080
	s_addc_u32 s48, s47, -1
	s_add_i32 s62, 0, 0x10000
	ds_read_b128 v[144:147], v141
	ds_read_b128 v[148:151], v141 offset:1024
	ds_read_b128 v[152:155], v141 offset:2048
	ds_read_b128 v[168:171], v141 offset:3072
	s_cmp_eq_u32 s13, 28
	s_cselect_b32 s51, s43, s48
	s_cselect_b32 s50, s42, s39
	s_cselect_b32 s49, s45, s12
	s_cselect_b32 s48, s44, s1
	ds_read_b128 v[172:175], v143
	ds_read_b128 v[176:179], v143 offset:1024
	ds_read_b128 v[180:183], v143 offset:2048
	ds_read_b128 v[184:187], v143 offset:3072
	ds_read_b128 v[188:191], v143 offset:4096
	ds_read_b128 v[192:195], v143 offset:5120
	ds_read_b128 v[196:199], v143 offset:6144
	ds_read_b128 v[224:227], v143 offset:7168
	s_add_i32 m0, s53, 0xc000
	s_nop 0
	global_load_lds_dwordx4 v136, s[46:47]
	s_add_i32 m0, s53, 0xe000
	s_nop 0
	global_load_lds_dwordx4 v138, s[46:47]
	s_add_i32 s39, 0, 0x14000
	s_add_i32 s62, s62, s52
	ds_read_b128 v[228:231], v141 offset:16384
	ds_read_b128 v[232:235], v141 offset:17408
	ds_read_b128 v[236:239], v141 offset:18432
	ds_read_b128 v[240:243], v141 offset:19456
	s_waitcnt lgkmcnt(0)
	s_barrier
	v_mfma_f32_16x16x32_bf16 v[126:129], v[144:147], v[172:175], v[126:129]
	v_mfma_f32_16x16x32_bf16 v[122:125], v[152:155], v[172:175], v[122:125]
	v_mfma_f32_16x16x32_bf16 v[118:121], v[144:147], v[180:183], v[118:121]
	v_mfma_f32_16x16x32_bf16 v[114:117], v[152:155], v[180:183], v[114:117]
	v_mfma_f32_16x16x32_bf16 v[102:105], v[144:147], v[188:191], v[102:105]
	v_mfma_f32_16x16x32_bf16 v[98:101], v[152:155], v[188:191], v[98:101]
	v_mfma_f32_16x16x32_bf16 v[86:89], v[144:147], v[196:199], v[86:89]
	v_mfma_f32_16x16x32_bf16 v[82:85], v[152:155], v[196:199], v[82:85]
	v_mfma_f32_16x16x32_bf16 v[126:129], v[148:151], v[176:179], v[126:129]
	v_mfma_f32_16x16x32_bf16 v[122:125], v[168:171], v[176:179], v[122:125]
	v_mfma_f32_16x16x32_bf16 v[118:121], v[148:151], v[184:187], v[118:121]
	v_mfma_f32_16x16x32_bf16 v[114:117], v[168:171], v[184:187], v[114:117]
	v_mfma_f32_16x16x32_bf16 v[102:105], v[148:151], v[192:195], v[102:105]
	v_mfma_f32_16x16x32_bf16 v[98:101], v[168:171], v[192:195], v[98:101]
	v_mfma_f32_16x16x32_bf16 v[86:89], v[148:151], v[224:227], v[86:89]
	v_mfma_f32_16x16x32_bf16 v[82:85], v[168:171], v[224:227], v[82:85]
	v_mfma_f32_16x16x32_bf16 v[110:113], v[228:231], v[172:175], v[110:113]
	v_mfma_f32_16x16x32_bf16 v[106:109], v[236:239], v[172:175], v[106:109]
	v_mfma_f32_16x16x32_bf16 v[94:97], v[228:231], v[180:183], v[94:97]
	v_mfma_f32_16x16x32_bf16 v[90:93], v[236:239], v[180:183], v[90:93]
	v_mfma_f32_16x16x32_bf16 v[78:81], v[228:231], v[188:191], v[78:81]
	v_mfma_f32_16x16x32_bf16 v[74:77], v[236:239], v[188:191], v[74:77]
	v_mfma_f32_16x16x32_bf16 v[70:73], v[228:231], v[196:199], v[70:73]
	v_mfma_f32_16x16x32_bf16 v[66:69], v[236:239], v[196:199], v[66:69]
	v_mfma_f32_16x16x32_bf16 v[110:113], v[232:235], v[176:179], v[110:113]
	v_mfma_f32_16x16x32_bf16 v[106:109], v[240:243], v[176:179], v[106:109]
	v_mfma_f32_16x16x32_bf16 v[94:97], v[232:235], v[184:187], v[94:97]
	v_mfma_f32_16x16x32_bf16 v[90:93], v[240:243], v[184:187], v[90:93]
	v_mfma_f32_16x16x32_bf16 v[78:81], v[232:235], v[192:195], v[78:81]
	v_mfma_f32_16x16x32_bf16 v[74:77], v[240:243], v[192:195], v[74:77]
	v_mfma_f32_16x16x32_bf16 v[70:73], v[232:235], v[224:227], v[70:73]
	v_mfma_f32_16x16x32_bf16 v[66:69], v[240:243], v[224:227], v[66:69]
	s_barrier
	s_mov_b32 m0, s53
	s_add_u32 s78, s50, s94
	s_addc_u32 s79, s51, s95
	ds_read_b128 v[172:175], v143 offset:16384
	ds_read_b128 v[176:179], v143 offset:17408
	ds_read_b128 v[180:183], v143 offset:18432
	ds_read_b128 v[184:187], v143 offset:19456
	ds_read_b128 v[188:191], v143 offset:20480
	ds_read_b128 v[192:195], v143 offset:21504
	ds_read_b128 v[196:199], v143 offset:22528
	ds_read_b128 v[224:227], v143 offset:23552
	global_load_lds_dwordx4 v134, s[50:51]
	s_mov_b32 m0, s54
	s_nop 0
	global_load_lds_dwordx4 v132, s[50:51]
	s_add_u32 s76, s48, s94
	s_addc_u32 s77, s49, s95
	s_mov_b32 m0, s62
	s_nop 0
	global_load_lds_dwordx4 v0, s[48:49]
	s_add_i32 m0, s62, 0x2000
	s_nop 0
	global_load_lds_dwordx4 v130, s[48:49]
	s_add_u32 s62, s48, 0x80000
	s_addc_u32 s63, s49, 0
	s_add_i32 s39, s39, s52
	s_mov_b32 m0, s39
	s_nop 0
	global_load_lds_dwordx4 v0, s[62:63]
	s_add_i32 m0, s39, 0x2000
	s_nop 0
	global_load_lds_dwordx4 v130, s[62:63]
	s_waitcnt vmcnt(6) lgkmcnt(0)
	s_barrier
	v_mfma_f32_16x16x32_bf16 v[62:65], v[144:147], v[172:175], v[62:65]
	v_mfma_f32_16x16x32_bf16 v[58:61], v[152:155], v[172:175], v[58:61]
	v_mfma_f32_16x16x32_bf16 v[54:57], v[144:147], v[180:183], v[54:57]
	v_mfma_f32_16x16x32_bf16 v[50:53], v[152:155], v[180:183], v[50:53]
	v_mfma_f32_16x16x32_bf16 v[38:41], v[144:147], v[188:191], v[38:41]
	v_mfma_f32_16x16x32_bf16 v[34:37], v[152:155], v[188:191], v[34:37]
	v_mfma_f32_16x16x32_bf16 v[22:25], v[144:147], v[196:199], v[22:25]
	v_mfma_f32_16x16x32_bf16 v[18:21], v[152:155], v[196:199], v[18:21]
	v_mfma_f32_16x16x32_bf16 v[62:65], v[148:151], v[176:179], v[62:65]
	v_mfma_f32_16x16x32_bf16 v[58:61], v[168:171], v[176:179], v[58:61]
	v_mfma_f32_16x16x32_bf16 v[54:57], v[148:151], v[184:187], v[54:57]
	v_mfma_f32_16x16x32_bf16 v[50:53], v[168:171], v[184:187], v[50:53]
	v_mfma_f32_16x16x32_bf16 v[38:41], v[148:151], v[192:195], v[38:41]
	v_mfma_f32_16x16x32_bf16 v[34:37], v[168:171], v[192:195], v[34:37]
	v_mfma_f32_16x16x32_bf16 v[22:25], v[148:151], v[224:227], v[22:25]
	v_mfma_f32_16x16x32_bf16 v[18:21], v[168:171], v[224:227], v[18:21]
	v_mfma_f32_16x16x32_bf16 v[46:49], v[228:231], v[172:175], v[46:49]
	v_mfma_f32_16x16x32_bf16 v[42:45], v[236:239], v[172:175], v[42:45]
	v_mfma_f32_16x16x32_bf16 v[30:33], v[228:231], v[180:183], v[30:33]
	v_mfma_f32_16x16x32_bf16 v[26:29], v[236:239], v[180:183], v[26:29]
	v_mfma_f32_16x16x32_bf16 v[14:17], v[228:231], v[188:191], v[14:17]
	v_mfma_f32_16x16x32_bf16 v[10:13], v[236:239], v[188:191], v[10:13]
	v_mfma_f32_16x16x32_bf16 v[6:9], v[228:231], v[196:199], v[6:9]
	v_mfma_f32_16x16x32_bf16 v[2:5], v[236:239], v[196:199], v[2:5]
	v_mfma_f32_16x16x32_bf16 v[46:49], v[232:235], v[176:179], v[46:49]
	v_mfma_f32_16x16x32_bf16 v[42:45], v[240:243], v[176:179], v[42:45]
	v_mfma_f32_16x16x32_bf16 v[30:33], v[232:235], v[184:187], v[30:33]
	v_mfma_f32_16x16x32_bf16 v[26:29], v[240:243], v[184:187], v[26:29]
	v_mfma_f32_16x16x32_bf16 v[14:17], v[232:235], v[192:195], v[14:17]
	v_mfma_f32_16x16x32_bf16 v[10:13], v[240:243], v[192:195], v[10:13]
	v_mfma_f32_16x16x32_bf16 v[6:9], v[232:235], v[224:227], v[6:9]
	v_mfma_f32_16x16x32_bf16 v[2:5], v[240:243], v[224:227], v[2:5]
	s_barrier
	s_add_i32 s39, 0, 0x18000
	ds_read_b128 v[144:147], v141 offset:32768
	ds_read_b128 v[148:151], v141 offset:33792
	ds_read_b128 v[152:155], v141 offset:34816
	ds_read_b128 v[168:171], v141 offset:35840
	s_add_u32 s50, s50, 0x80000
	s_addc_u32 s51, s51, 0
	ds_read_b128 v[172:175], v143 offset:32768
	ds_read_b128 v[176:179], v143 offset:33792
	ds_read_b128 v[180:183], v143 offset:34816
	ds_read_b128 v[184:187], v143 offset:35840
	ds_read_b128 v[188:191], v143 offset:36864
	ds_read_b128 v[192:195], v143 offset:37888
	ds_read_b128 v[196:199], v143 offset:38912
	ds_read_b128 v[224:227], v143 offset:39936
	s_mov_b32 m0, s55
	s_nop 0
	global_load_lds_dwordx4 v134, s[50:51]
	s_mov_b32 m0, s56
	s_nop 0
	global_load_lds_dwordx4 v132, s[50:51]
	s_add_i32 s50, 0, 0x1c000
	s_add_i32 s39, s39, s52
	ds_read_b128 v[228:231], v141 offset:49152
	ds_read_b128 v[232:235], v141 offset:50176
	ds_read_b128 v[236:239], v141 offset:51200
	ds_read_b128 v[240:243], v141 offset:52224
	s_waitcnt lgkmcnt(0)
	s_barrier
	v_mfma_f32_16x16x32_bf16 v[126:129], v[144:147], v[172:175], v[126:129]
	v_mfma_f32_16x16x32_bf16 v[122:125], v[152:155], v[172:175], v[122:125]
	v_mfma_f32_16x16x32_bf16 v[118:121], v[144:147], v[180:183], v[118:121]
	v_mfma_f32_16x16x32_bf16 v[114:117], v[152:155], v[180:183], v[114:117]
	v_mfma_f32_16x16x32_bf16 v[102:105], v[144:147], v[188:191], v[102:105]
	v_mfma_f32_16x16x32_bf16 v[98:101], v[152:155], v[188:191], v[98:101]
	v_mfma_f32_16x16x32_bf16 v[86:89], v[144:147], v[196:199], v[86:89]
	v_mfma_f32_16x16x32_bf16 v[82:85], v[152:155], v[196:199], v[82:85]
	v_mfma_f32_16x16x32_bf16 v[126:129], v[148:151], v[176:179], v[126:129]
	v_mfma_f32_16x16x32_bf16 v[122:125], v[168:171], v[176:179], v[122:125]
	v_mfma_f32_16x16x32_bf16 v[118:121], v[148:151], v[184:187], v[118:121]
	v_mfma_f32_16x16x32_bf16 v[114:117], v[168:171], v[184:187], v[114:117]
	v_mfma_f32_16x16x32_bf16 v[102:105], v[148:151], v[192:195], v[102:105]
	v_mfma_f32_16x16x32_bf16 v[98:101], v[168:171], v[192:195], v[98:101]
	v_mfma_f32_16x16x32_bf16 v[86:89], v[148:151], v[224:227], v[86:89]
	v_mfma_f32_16x16x32_bf16 v[82:85], v[168:171], v[224:227], v[82:85]
	v_mfma_f32_16x16x32_bf16 v[110:113], v[228:231], v[172:175], v[110:113]
	v_mfma_f32_16x16x32_bf16 v[106:109], v[236:239], v[172:175], v[106:109]
	v_mfma_f32_16x16x32_bf16 v[94:97], v[228:231], v[180:183], v[94:97]
	v_mfma_f32_16x16x32_bf16 v[90:93], v[236:239], v[180:183], v[90:93]
	v_mfma_f32_16x16x32_bf16 v[78:81], v[228:231], v[188:191], v[78:81]
	v_mfma_f32_16x16x32_bf16 v[74:77], v[236:239], v[188:191], v[74:77]
	v_mfma_f32_16x16x32_bf16 v[70:73], v[228:231], v[196:199], v[70:73]
	v_mfma_f32_16x16x32_bf16 v[66:69], v[236:239], v[196:199], v[66:69]
	v_mfma_f32_16x16x32_bf16 v[110:113], v[232:235], v[176:179], v[110:113]
	v_mfma_f32_16x16x32_bf16 v[106:109], v[240:243], v[176:179], v[106:109]
	v_mfma_f32_16x16x32_bf16 v[94:97], v[232:235], v[184:187], v[94:97]
	v_mfma_f32_16x16x32_bf16 v[90:93], v[240:243], v[184:187], v[90:93]
	v_mfma_f32_16x16x32_bf16 v[78:81], v[232:235], v[192:195], v[78:81]
	v_mfma_f32_16x16x32_bf16 v[74:77], v[240:243], v[192:195], v[74:77]
	v_mfma_f32_16x16x32_bf16 v[70:73], v[232:235], v[224:227], v[70:73]
	v_mfma_f32_16x16x32_bf16 v[66:69], v[240:243], v[224:227], v[66:69]
	s_barrier
	s_mov_b32 m0, s57
	ds_read_b128 v[172:175], v143 offset:49152
	ds_read_b128 v[176:179], v143 offset:50176
	ds_read_b128 v[180:183], v143 offset:51200
	ds_read_b128 v[184:187], v143 offset:52224
	ds_read_b128 v[188:191], v143 offset:53248
	ds_read_b128 v[192:195], v143 offset:54272
	ds_read_b128 v[196:199], v143 offset:55296
	ds_read_b128 v[224:227], v143 offset:56320
	global_load_lds_dwordx4 v134, s[78:79]
	s_mov_b32 m0, s58
	s_nop 0
	global_load_lds_dwordx4 v132, s[78:79]
	s_mov_b32 m0, s39
	s_nop 0
	global_load_lds_dwordx4 v0, s[76:77]
	s_add_i32 m0, s39, 0x2000
	s_nop 0
	global_load_lds_dwordx4 v130, s[76:77]
	s_add_u32 s48, s48, 0x80080
	s_addc_u32 s49, s49, 0
	s_add_i32 s39, s50, s52
	s_mov_b32 m0, s39
	s_nop 0
	global_load_lds_dwordx4 v0, s[48:49]
	s_add_i32 m0, s39, 0x2000
	s_nop 0
	global_load_lds_dwordx4 v130, s[48:49]
	s_waitcnt vmcnt(6) lgkmcnt(0)
	s_barrier
	v_mfma_f32_16x16x32_bf16 v[62:65], v[144:147], v[172:175], v[62:65]
	v_mfma_f32_16x16x32_bf16 v[58:61], v[152:155], v[172:175], v[58:61]
	v_mfma_f32_16x16x32_bf16 v[54:57], v[144:147], v[180:183], v[54:57]
	v_mfma_f32_16x16x32_bf16 v[50:53], v[152:155], v[180:183], v[50:53]
	v_mfma_f32_16x16x32_bf16 v[38:41], v[144:147], v[188:191], v[38:41]
	v_mfma_f32_16x16x32_bf16 v[34:37], v[152:155], v[188:191], v[34:37]
	v_mfma_f32_16x16x32_bf16 v[22:25], v[144:147], v[196:199], v[22:25]
	v_mfma_f32_16x16x32_bf16 v[18:21], v[152:155], v[196:199], v[18:21]
	v_mfma_f32_16x16x32_bf16 v[62:65], v[148:151], v[176:179], v[62:65]
	v_mfma_f32_16x16x32_bf16 v[58:61], v[168:171], v[176:179], v[58:61]
	v_mfma_f32_16x16x32_bf16 v[54:57], v[148:151], v[184:187], v[54:57]
	v_mfma_f32_16x16x32_bf16 v[50:53], v[168:171], v[184:187], v[50:53]
	v_mfma_f32_16x16x32_bf16 v[38:41], v[148:151], v[192:195], v[38:41]
	v_mfma_f32_16x16x32_bf16 v[34:37], v[168:171], v[192:195], v[34:37]
	v_mfma_f32_16x16x32_bf16 v[22:25], v[148:151], v[224:227], v[22:25]
	v_mfma_f32_16x16x32_bf16 v[18:21], v[168:171], v[224:227], v[18:21]
	v_mfma_f32_16x16x32_bf16 v[46:49], v[228:231], v[172:175], v[46:49]
	v_mfma_f32_16x16x32_bf16 v[42:45], v[236:239], v[172:175], v[42:45]
	v_mfma_f32_16x16x32_bf16 v[30:33], v[228:231], v[180:183], v[30:33]
	v_mfma_f32_16x16x32_bf16 v[26:29], v[236:239], v[180:183], v[26:29]
	v_mfma_f32_16x16x32_bf16 v[14:17], v[228:231], v[188:191], v[14:17]
	v_mfma_f32_16x16x32_bf16 v[10:13], v[236:239], v[188:191], v[10:13]
	v_mfma_f32_16x16x32_bf16 v[6:9], v[228:231], v[196:199], v[6:9]
	v_mfma_f32_16x16x32_bf16 v[2:5], v[236:239], v[196:199], v[2:5]
	v_mfma_f32_16x16x32_bf16 v[46:49], v[232:235], v[176:179], v[46:49]
	v_mfma_f32_16x16x32_bf16 v[42:45], v[240:243], v[176:179], v[42:45]
	v_mfma_f32_16x16x32_bf16 v[30:33], v[232:235], v[184:187], v[30:33]
	v_mfma_f32_16x16x32_bf16 v[26:29], v[240:243], v[184:187], v[26:29]
	v_mfma_f32_16x16x32_bf16 v[14:17], v[232:235], v[192:195], v[14:17]
	v_mfma_f32_16x16x32_bf16 v[10:13], v[240:243], v[192:195], v[10:13]
	v_mfma_f32_16x16x32_bf16 v[6:9], v[232:235], v[224:227], v[6:9]
	v_mfma_f32_16x16x32_bf16 v[2:5], v[240:243], v[224:227], v[2:5]
	s_barrier
	s_add_i32 s13, s13, 2
	s_add_u32 s46, s46, 0x100
	s_addc_u32 s47, s47, 0
	s_add_u32 s1, s1, 0x100
	s_addc_u32 s12, s12, 0
	s_cmp_gt_u32 s13, 29
	s_cbranch_scc0 .LBB0_234
	v_readlane_b32 s6, v255, 23
	v_lshl_add_u32 v150, s61, 8, v140
	v_lshl_or_b32 v144, s60, 8, v142
	v_readlane_b32 s7, v255, 24
	v_ashrrev_i32_e32 v145, 31, v144
	s_movk_i32 s1, 0x5800
	v_mov_b64_e32 v[146:147], s[6:7]
	v_cvt_pk_bf16_f32 v70, v70, v71
	v_cvt_pk_bf16_f32 v71, v72, v73
	v_cvt_pk_bf16_f32 v72, v66, v67
	v_add_u32_e32 v66, 0x80, v150
	v_mad_i64_i32 v[148:149], s[12:13], v150, s1, v[146:147]
	v_lshlrev_b64 v[144:145], 1, v[144:145]
	v_cvt_pk_bf16_f32 v110, v110, v111
	v_cvt_pk_bf16_f32 v111, v112, v113
	v_cvt_pk_bf16_f32 v112, v106, v107
	v_or_b32_e32 v106, 16, v150
	v_mad_i64_i32 v[66:67], s[12:13], v66, s1, v[146:147]
	v_cvt_pk_bf16_f32 v46, v46, v47
	v_cvt_pk_bf16_f32 v47, v48, v49
	v_cvt_pk_bf16_f32 v48, v42, v43
	v_add_u32_e32 v42, 0x90, v150
	v_lshl_add_u64 v[148:149], v[148:149], 0, v[144:145]
	v_cvt_pk_bf16_f32 v113, v108, v109
	v_mad_i64_i32 v[106:107], s[12:13], v106, s1, v[146:147]
	v_cvt_pk_bf16_f32 v94, v94, v95
	v_cvt_pk_bf16_f32 v95, v96, v97
	v_cvt_pk_bf16_f32 v96, v90, v91
	v_or_b32_e32 v90, 32, v150
	v_lshl_add_u64 v[66:67], v[66:67], 0, v[144:145]
	v_cvt_pk_bf16_f32 v49, v44, v45
	v_mad_i64_i32 v[42:43], s[12:13], v42, s1, v[146:147]
	v_cvt_pk_bf16_f32 v30, v30, v31
	v_cvt_pk_bf16_f32 v31, v32, v33
	v_cvt_pk_bf16_f32 v32, v26, v27
	v_add_u32_e32 v26, 0xa0, v150
	global_store_dwordx4 v[148:149], v[110:113], off offset:256
	v_cvt_pk_bf16_f32 v97, v92, v93
	v_mad_i64_i32 v[90:91], s[12:13], v90, s1, v[146:147]
	v_lshl_add_u64 v[110:111], v[106:107], 0, v[144:145]
	v_cvt_pk_bf16_f32 v78, v78, v79
	v_cvt_pk_bf16_f32 v79, v80, v81
	v_cvt_pk_bf16_f32 v80, v74, v75
	v_or_b32_e32 v74, 48, v150
	global_store_dwordx4 v[66:67], v[46:49], off offset:256
	v_cvt_pk_bf16_f32 v33, v28, v29
	v_mad_i64_i32 v[26:27], s[12:13], v26, s1, v[146:147]
	v_lshl_add_u64 v[46:47], v[42:43], 0, v[144:145]
	v_cvt_pk_bf16_f32 v14, v14, v15
	v_cvt_pk_bf16_f32 v15, v16, v17
	v_cvt_pk_bf16_f32 v16, v10, v11
	v_add_u32_e32 v10, 0xb0, v150
	global_store_dwordx4 v[110:111], v[94:97], off offset:256
	v_cvt_pk_bf16_f32 v81, v76, v77
	v_mad_i64_i32 v[74:75], s[12:13], v74, s1, v[146:147]
	v_lshl_add_u64 v[94:95], v[90:91], 0, v[144:145]
	global_store_dwordx4 v[46:47], v[30:33], off offset:256
	v_cvt_pk_bf16_f32 v17, v12, v13
	v_mad_i64_i32 v[10:11], s[12:13], v10, s1, v[146:147]
	v_lshl_add_u64 v[30:31], v[26:27], 0, v[144:145]
	v_cvt_pk_bf16_f32 v126, v126, v127
	v_cvt_pk_bf16_f32 v127, v128, v129
	v_cvt_pk_bf16_f32 v128, v122, v123
	v_cvt_pk_bf16_f32 v129, v124, v125
	v_cvt_pk_bf16_f32 v106, v118, v119
	v_cvt_pk_bf16_f32 v107, v120, v121
	v_cvt_pk_bf16_f32 v108, v114, v115
	v_cvt_pk_bf16_f32 v109, v116, v117
	v_cvt_pk_bf16_f32 v90, v102, v103
	v_cvt_pk_bf16_f32 v91, v104, v105
	v_cvt_pk_bf16_f32 v92, v98, v99
	v_cvt_pk_bf16_f32 v93, v100, v101
	global_store_dwordx4 v[94:95], v[78:81], off offset:256
	v_cvt_pk_bf16_f32 v76, v82, v83
	v_cvt_pk_bf16_f32 v77, v84, v85
	v_lshl_add_u64 v[78:79], v[74:75], 0, v[144:145]
	v_cvt_pk_bf16_f32 v74, v86, v87
	v_cvt_pk_bf16_f32 v75, v88, v89
	v_cvt_pk_bf16_f32 v73, v68, v69
	v_cvt_pk_bf16_f32 v62, v62, v63
	v_cvt_pk_bf16_f32 v63, v64, v65
	v_cvt_pk_bf16_f32 v64, v58, v59
	v_cvt_pk_bf16_f32 v65, v60, v61
	v_cvt_pk_bf16_f32 v42, v54, v55
	v_cvt_pk_bf16_f32 v43, v56, v57
	v_cvt_pk_bf16_f32 v44, v50, v51
	v_cvt_pk_bf16_f32 v45, v52, v53
	v_cvt_pk_bf16_f32 v26, v38, v39
	v_cvt_pk_bf16_f32 v27, v40, v41
	v_cvt_pk_bf16_f32 v28, v34, v35
	v_cvt_pk_bf16_f32 v29, v36, v37
	global_store_dwordx4 v[30:31], v[14:17], off offset:256
	v_cvt_pk_bf16_f32 v12, v18, v19
	v_cvt_pk_bf16_f32 v13, v20, v21
	v_lshl_add_u64 v[14:15], v[10:11], 0, v[144:145]
	v_cvt_pk_bf16_f32 v10, v22, v23
	v_cvt_pk_bf16_f32 v11, v24, v25
	v_cvt_pk_bf16_f32 v6, v6, v7
	v_cvt_pk_bf16_f32 v7, v8, v9
	v_cvt_pk_bf16_f32 v8, v2, v3
	v_cvt_pk_bf16_f32 v9, v4, v5
	s_and_b64 vcc, exec, s[40:41]
	s_mov_b32 s60, s0
	s_mov_b32 s61, s38
	s_mov_b64 s[48:49], s[44:45]
	s_mov_b64 s[46:47], s[42:43]
	global_store_dwordx4 v[148:149], v[126:129], off
	global_store_dwordx4 v[110:111], v[106:109], off
	global_store_dwordx4 v[94:95], v[90:93], off
	global_store_dwordx4 v[78:79], v[74:77], off
	global_store_dwordx4 v[78:79], v[70:73], off offset:256
	global_store_dwordx4 v[66:67], v[62:65], off
	global_store_dwordx4 v[46:47], v[42:45], off
	global_store_dwordx4 v[30:31], v[26:29], off
	global_store_dwordx4 v[14:15], v[10:13], off
	global_store_dwordx4 v[14:15], v[6:9], off offset:256
	s_cbranch_vccz .LBB0_227
	s_waitcnt vmcnt(0)
	v_readlane_b32 s60, v255, 21
	s_cmpk_gt_u32 s36, 0xff
	s_mov_b32 s18, s60
	v_readlane_b32 s61, v255, 22
	s_cbranch_scc1 .LBB0_238
	s_barrier

.LBB0_282:
	s_add_i32 s67, s50, 2
	s_add_u32 s51, s0, 0xfff80080
	s_addc_u32 s52, s1, -1
	s_add_i32 s68, 0, 0x10000
	ds_read_b128 v[136:139], v153
	ds_read_b128 v[140:143], v153 offset:1024
	ds_read_b128 v[144:147], v153 offset:2048
	ds_read_b128 v[148:151], v153 offset:3072
	s_cmp_eq_u32 s12, s50
	s_cselect_b32 s50, s48, s13
	s_cselect_b32 s53, s47, s52
	s_cselect_b32 s52, s46, s51
	s_cselect_b32 s51, s49, s66
	ds_read_b128 v[168:171], v155
	ds_read_b128 v[172:175], v155 offset:1024
	ds_read_b128 v[176:179], v155 offset:2048
	ds_read_b128 v[180:183], v155 offset:3072
	ds_read_b128 v[184:187], v155 offset:4096
	ds_read_b128 v[188:191], v155 offset:5120
	ds_read_b128 v[192:195], v155 offset:6144
	ds_read_b128 v[196:199], v155 offset:7168
	s_add_i32 m0, s55, 0xc000
	s_nop 0
	global_load_lds_dwordx4 v132, s[0:1]
	s_add_i32 m0, s55, 0xe000
	s_nop 0
	global_load_lds_dwordx4 v134, s[0:1]
	s_add_i32 s70, 0, 0x14000
	s_add_i32 s68, s68, s54
	ds_read_b128 v[224:227], v153 offset:16384
	ds_read_b128 v[228:231], v153 offset:17408
	ds_read_b128 v[232:235], v153 offset:18432
	ds_read_b128 v[236:239], v153 offset:19456
	s_waitcnt lgkmcnt(0)
	s_barrier
	v_mfma_f32_16x16x32_bf16 v[126:129], v[136:139], v[168:171], v[126:129]
	v_mfma_f32_16x16x32_bf16 v[122:125], v[144:147], v[168:171], v[122:125]
	v_mfma_f32_16x16x32_bf16 v[110:113], v[136:139], v[176:179], v[110:113]
	v_mfma_f32_16x16x32_bf16 v[106:109], v[144:147], v[176:179], v[106:109]
	v_mfma_f32_16x16x32_bf16 v[94:97], v[136:139], v[184:187], v[94:97]
	v_mfma_f32_16x16x32_bf16 v[90:93], v[144:147], v[184:187], v[90:93]
	v_mfma_f32_16x16x32_bf16 v[78:81], v[136:139], v[192:195], v[78:81]
	v_mfma_f32_16x16x32_bf16 v[74:77], v[144:147], v[192:195], v[74:77]
	v_mfma_f32_16x16x32_bf16 v[126:129], v[140:143], v[172:175], v[126:129]
	v_mfma_f32_16x16x32_bf16 v[122:125], v[148:151], v[172:175], v[122:125]
	v_mfma_f32_16x16x32_bf16 v[110:113], v[140:143], v[180:183], v[110:113]
	v_mfma_f32_16x16x32_bf16 v[106:109], v[148:151], v[180:183], v[106:109]
	v_mfma_f32_16x16x32_bf16 v[94:97], v[140:143], v[188:191], v[94:97]
	v_mfma_f32_16x16x32_bf16 v[90:93], v[148:151], v[188:191], v[90:93]
	v_mfma_f32_16x16x32_bf16 v[78:81], v[140:143], v[196:199], v[78:81]
	v_mfma_f32_16x16x32_bf16 v[74:77], v[148:151], v[196:199], v[74:77]
	v_mfma_f32_16x16x32_bf16 v[118:121], v[224:227], v[168:171], v[118:121]
	v_mfma_f32_16x16x32_bf16 v[114:117], v[232:235], v[168:171], v[114:117]
	v_mfma_f32_16x16x32_bf16 v[102:105], v[224:227], v[176:179], v[102:105]
	v_mfma_f32_16x16x32_bf16 v[98:101], v[232:235], v[176:179], v[98:101]
	v_mfma_f32_16x16x32_bf16 v[86:89], v[224:227], v[184:187], v[86:89]
	v_mfma_f32_16x16x32_bf16 v[82:85], v[232:235], v[184:187], v[82:85]
	v_mfma_f32_16x16x32_bf16 v[70:73], v[224:227], v[192:195], v[70:73]
	v_mfma_f32_16x16x32_bf16 v[66:69], v[232:235], v[192:195], v[66:69]
	v_mfma_f32_16x16x32_bf16 v[118:121], v[228:231], v[172:175], v[118:121]
	v_mfma_f32_16x16x32_bf16 v[114:117], v[236:239], v[172:175], v[114:117]
	v_mfma_f32_16x16x32_bf16 v[102:105], v[228:231], v[180:183], v[102:105]
	v_mfma_f32_16x16x32_bf16 v[98:101], v[236:239], v[180:183], v[98:101]
	v_mfma_f32_16x16x32_bf16 v[86:89], v[228:231], v[188:191], v[86:89]
	v_mfma_f32_16x16x32_bf16 v[82:85], v[236:239], v[188:191], v[82:85]
	v_mfma_f32_16x16x32_bf16 v[70:73], v[228:231], v[196:199], v[70:73]
	v_mfma_f32_16x16x32_bf16 v[66:69], v[236:239], v[196:199], v[66:69]
	s_barrier
	s_mov_b32 m0, s55
	s_add_u32 s78, s52, s94
	s_addc_u32 s79, s53, s95
	ds_read_b128 v[168:171], v155 offset:16384
	ds_read_b128 v[172:175], v155 offset:17408
	ds_read_b128 v[176:179], v155 offset:18432
	ds_read_b128 v[180:183], v155 offset:19456
	ds_read_b128 v[184:187], v155 offset:20480
	ds_read_b128 v[188:191], v155 offset:21504
	ds_read_b128 v[192:195], v155 offset:22528
	ds_read_b128 v[196:199], v155 offset:23552
	global_load_lds_dwordx4 v0, s[52:53]
	s_mov_b32 m0, s56
	s_nop 0
	global_load_lds_dwordx4 v130, s[52:53]
	s_add_u32 s76, s50, s94
	s_addc_u32 s77, s51, s95
	s_mov_b32 m0, s68
	s_nop 0
	global_load_lds_dwordx4 v0, s[50:51]
	s_add_i32 m0, s68, 0x2000
	s_nop 0
	global_load_lds_dwordx4 v130, s[50:51]
	s_add_u32 s68, s50, 0x80000
	s_addc_u32 s69, s51, 0
	s_add_i32 s70, s70, s54
	s_mov_b32 m0, s70
	s_nop 0
	global_load_lds_dwordx4 v0, s[68:69]
	s_add_i32 m0, s70, 0x2000
	s_nop 0
	global_load_lds_dwordx4 v130, s[68:69]
	s_waitcnt vmcnt(6) lgkmcnt(0)
	s_barrier
	v_mfma_f32_16x16x32_bf16 v[62:65], v[136:139], v[168:171], v[62:65]
	v_mfma_f32_16x16x32_bf16 v[58:61], v[144:147], v[168:171], v[58:61]
	v_mfma_f32_16x16x32_bf16 v[46:49], v[136:139], v[176:179], v[46:49]
	v_mfma_f32_16x16x32_bf16 v[42:45], v[144:147], v[176:179], v[42:45]
	v_mfma_f32_16x16x32_bf16 v[30:33], v[136:139], v[184:187], v[30:33]
	v_mfma_f32_16x16x32_bf16 v[26:29], v[144:147], v[184:187], v[26:29]
	v_mfma_f32_16x16x32_bf16 v[14:17], v[136:139], v[192:195], v[14:17]
	v_mfma_f32_16x16x32_bf16 v[10:13], v[144:147], v[192:195], v[10:13]
	v_mfma_f32_16x16x32_bf16 v[62:65], v[140:143], v[172:175], v[62:65]
	v_mfma_f32_16x16x32_bf16 v[58:61], v[148:151], v[172:175], v[58:61]
	v_mfma_f32_16x16x32_bf16 v[46:49], v[140:143], v[180:183], v[46:49]
	v_mfma_f32_16x16x32_bf16 v[42:45], v[148:151], v[180:183], v[42:45]
	v_mfma_f32_16x16x32_bf16 v[30:33], v[140:143], v[188:191], v[30:33]
	v_mfma_f32_16x16x32_bf16 v[26:29], v[148:151], v[188:191], v[26:29]
	v_mfma_f32_16x16x32_bf16 v[14:17], v[140:143], v[196:199], v[14:17]
	v_mfma_f32_16x16x32_bf16 v[10:13], v[148:151], v[196:199], v[10:13]
	v_mfma_f32_16x16x32_bf16 v[54:57], v[224:227], v[168:171], v[54:57]
	v_mfma_f32_16x16x32_bf16 v[50:53], v[232:235], v[168:171], v[50:53]
	v_mfma_f32_16x16x32_bf16 v[38:41], v[224:227], v[176:179], v[38:41]
	v_mfma_f32_16x16x32_bf16 v[34:37], v[232:235], v[176:179], v[34:37]
	v_mfma_f32_16x16x32_bf16 v[22:25], v[224:227], v[184:187], v[22:25]
	v_mfma_f32_16x16x32_bf16 v[18:21], v[232:235], v[184:187], v[18:21]
	v_mfma_f32_16x16x32_bf16 v[6:9], v[224:227], v[192:195], v[6:9]
	v_mfma_f32_16x16x32_bf16 v[2:5], v[232:235], v[192:195], v[2:5]
	v_mfma_f32_16x16x32_bf16 v[54:57], v[228:231], v[172:175], v[54:57]
	v_mfma_f32_16x16x32_bf16 v[50:53], v[236:239], v[172:175], v[50:53]
	v_mfma_f32_16x16x32_bf16 v[38:41], v[228:231], v[180:183], v[38:41]
	v_mfma_f32_16x16x32_bf16 v[34:37], v[236:239], v[180:183], v[34:37]
	v_mfma_f32_16x16x32_bf16 v[22:25], v[228:231], v[188:191], v[22:25]
	v_mfma_f32_16x16x32_bf16 v[18:21], v[236:239], v[188:191], v[18:21]
	v_mfma_f32_16x16x32_bf16 v[6:9], v[228:231], v[196:199], v[6:9]
	v_mfma_f32_16x16x32_bf16 v[2:5], v[236:239], v[196:199], v[2:5]
	s_barrier
	s_add_i32 s68, 0, 0x18000
	ds_read_b128 v[136:139], v153 offset:32768
	ds_read_b128 v[140:143], v153 offset:33792
	ds_read_b128 v[144:147], v153 offset:34816
	ds_read_b128 v[148:151], v153 offset:35840
	s_add_u32 s52, s52, 0x80000
	s_addc_u32 s53, s53, 0
	ds_read_b128 v[168:171], v155 offset:32768
	ds_read_b128 v[172:175], v155 offset:33792
	ds_read_b128 v[176:179], v155 offset:34816
	ds_read_b128 v[180:183], v155 offset:35840
	ds_read_b128 v[184:187], v155 offset:36864
	ds_read_b128 v[188:191], v155 offset:37888
	ds_read_b128 v[192:195], v155 offset:38912
	ds_read_b128 v[196:199], v155 offset:39936
	s_mov_b32 m0, s57
	s_nop 0
	global_load_lds_dwordx4 v0, s[52:53]
	s_mov_b32 m0, s58
	s_nop 0
	global_load_lds_dwordx4 v130, s[52:53]
	s_add_i32 s52, 0, 0x1c000
	s_add_i32 s53, s68, s54
	ds_read_b128 v[224:227], v153 offset:49152
	ds_read_b128 v[228:231], v153 offset:50176
	ds_read_b128 v[232:235], v153 offset:51200
	ds_read_b128 v[236:239], v153 offset:52224
	s_waitcnt lgkmcnt(0)
	s_barrier
	v_mfma_f32_16x16x32_bf16 v[126:129], v[136:139], v[168:171], v[126:129]
	v_mfma_f32_16x16x32_bf16 v[122:125], v[144:147], v[168:171], v[122:125]
	v_mfma_f32_16x16x32_bf16 v[110:113], v[136:139], v[176:179], v[110:113]
	v_mfma_f32_16x16x32_bf16 v[106:109], v[144:147], v[176:179], v[106:109]
	v_mfma_f32_16x16x32_bf16 v[94:97], v[136:139], v[184:187], v[94:97]
	v_mfma_f32_16x16x32_bf16 v[90:93], v[144:147], v[184:187], v[90:93]
	v_mfma_f32_16x16x32_bf16 v[78:81], v[136:139], v[192:195], v[78:81]
	v_mfma_f32_16x16x32_bf16 v[74:77], v[144:147], v[192:195], v[74:77]
	v_mfma_f32_16x16x32_bf16 v[126:129], v[140:143], v[172:175], v[126:129]
	v_mfma_f32_16x16x32_bf16 v[122:125], v[148:151], v[172:175], v[122:125]
	v_mfma_f32_16x16x32_bf16 v[110:113], v[140:143], v[180:183], v[110:113]
	v_mfma_f32_16x16x32_bf16 v[106:109], v[148:151], v[180:183], v[106:109]
	v_mfma_f32_16x16x32_bf16 v[94:97], v[140:143], v[188:191], v[94:97]
	v_mfma_f32_16x16x32_bf16 v[90:93], v[148:151], v[188:191], v[90:93]
	v_mfma_f32_16x16x32_bf16 v[78:81], v[140:143], v[196:199], v[78:81]
	v_mfma_f32_16x16x32_bf16 v[74:77], v[148:151], v[196:199], v[74:77]
	v_mfma_f32_16x16x32_bf16 v[118:121], v[224:227], v[168:171], v[118:121]
	v_mfma_f32_16x16x32_bf16 v[114:117], v[232:235], v[168:171], v[114:117]
	v_mfma_f32_16x16x32_bf16 v[102:105], v[224:227], v[176:179], v[102:105]
	v_mfma_f32_16x16x32_bf16 v[98:101], v[232:235], v[176:179], v[98:101]
	v_mfma_f32_16x16x32_bf16 v[86:89], v[224:227], v[184:187], v[86:89]
	v_mfma_f32_16x16x32_bf16 v[82:85], v[232:235], v[184:187], v[82:85]
	v_mfma_f32_16x16x32_bf16 v[70:73], v[224:227], v[192:195], v[70:73]
	v_mfma_f32_16x16x32_bf16 v[66:69], v[232:235], v[192:195], v[66:69]
	v_mfma_f32_16x16x32_bf16 v[118:121], v[228:231], v[172:175], v[118:121]
	v_mfma_f32_16x16x32_bf16 v[114:117], v[236:239], v[172:175], v[114:117]
	v_mfma_f32_16x16x32_bf16 v[102:105], v[228:231], v[180:183], v[102:105]
	v_mfma_f32_16x16x32_bf16 v[98:101], v[236:239], v[180:183], v[98:101]
	v_mfma_f32_16x16x32_bf16 v[86:89], v[228:231], v[188:191], v[86:89]
	v_mfma_f32_16x16x32_bf16 v[82:85], v[236:239], v[188:191], v[82:85]
	v_mfma_f32_16x16x32_bf16 v[70:73], v[228:231], v[196:199], v[70:73]
	v_mfma_f32_16x16x32_bf16 v[66:69], v[236:239], v[196:199], v[66:69]
	s_barrier
	s_mov_b32 m0, s59
	ds_read_b128 v[168:171], v155 offset:49152
	ds_read_b128 v[172:175], v155 offset:50176
	ds_read_b128 v[176:179], v155 offset:51200
	ds_read_b128 v[180:183], v155 offset:52224
	ds_read_b128 v[184:187], v155 offset:53248
	ds_read_b128 v[188:191], v155 offset:54272
	ds_read_b128 v[192:195], v155 offset:55296
	ds_read_b128 v[196:199], v155 offset:56320
	global_load_lds_dwordx4 v0, s[78:79]
	s_mov_b32 m0, s60
	s_nop 0
	global_load_lds_dwordx4 v130, s[78:79]
	s_mov_b32 m0, s53
	s_nop 0
	global_load_lds_dwordx4 v0, s[76:77]
	s_add_i32 m0, s53, 0x2000
	s_nop 0
	global_load_lds_dwordx4 v130, s[76:77]
	s_add_u32 s50, s50, 0x80080
	s_addc_u32 s51, s51, 0
	s_add_i32 s52, s52, s54
	s_mov_b32 m0, s52
	s_nop 0
	global_load_lds_dwordx4 v0, s[50:51]
	s_add_i32 m0, s52, 0x2000
	s_nop 0
	global_load_lds_dwordx4 v130, s[50:51]
	s_waitcnt vmcnt(6) lgkmcnt(0)
	s_barrier
	v_mfma_f32_16x16x32_bf16 v[62:65], v[136:139], v[168:171], v[62:65]
	v_mfma_f32_16x16x32_bf16 v[58:61], v[144:147], v[168:171], v[58:61]
	v_mfma_f32_16x16x32_bf16 v[46:49], v[136:139], v[176:179], v[46:49]
	v_mfma_f32_16x16x32_bf16 v[42:45], v[144:147], v[176:179], v[42:45]
	v_mfma_f32_16x16x32_bf16 v[30:33], v[136:139], v[184:187], v[30:33]
	v_mfma_f32_16x16x32_bf16 v[26:29], v[144:147], v[184:187], v[26:29]
	v_mfma_f32_16x16x32_bf16 v[14:17], v[136:139], v[192:195], v[14:17]
	v_mfma_f32_16x16x32_bf16 v[10:13], v[144:147], v[192:195], v[10:13]
	v_mfma_f32_16x16x32_bf16 v[62:65], v[140:143], v[172:175], v[62:65]
	v_mfma_f32_16x16x32_bf16 v[58:61], v[148:151], v[172:175], v[58:61]
	v_mfma_f32_16x16x32_bf16 v[46:49], v[140:143], v[180:183], v[46:49]
	v_mfma_f32_16x16x32_bf16 v[42:45], v[148:151], v[180:183], v[42:45]
	v_mfma_f32_16x16x32_bf16 v[30:33], v[140:143], v[188:191], v[30:33]
	v_mfma_f32_16x16x32_bf16 v[26:29], v[148:151], v[188:191], v[26:29]
	v_mfma_f32_16x16x32_bf16 v[14:17], v[140:143], v[196:199], v[14:17]
	v_mfma_f32_16x16x32_bf16 v[10:13], v[148:151], v[196:199], v[10:13]
	v_mfma_f32_16x16x32_bf16 v[54:57], v[224:227], v[168:171], v[54:57]
	v_mfma_f32_16x16x32_bf16 v[50:53], v[232:235], v[168:171], v[50:53]
	v_mfma_f32_16x16x32_bf16 v[38:41], v[224:227], v[176:179], v[38:41]
	v_mfma_f32_16x16x32_bf16 v[34:37], v[232:235], v[176:179], v[34:37]
	v_mfma_f32_16x16x32_bf16 v[22:25], v[224:227], v[184:187], v[22:25]
	v_mfma_f32_16x16x32_bf16 v[18:21], v[232:235], v[184:187], v[18:21]
	v_mfma_f32_16x16x32_bf16 v[6:9], v[224:227], v[192:195], v[6:9]
	v_mfma_f32_16x16x32_bf16 v[2:5], v[232:235], v[192:195], v[2:5]
	v_mfma_f32_16x16x32_bf16 v[54:57], v[228:231], v[172:175], v[54:57]
	v_mfma_f32_16x16x32_bf16 v[50:53], v[236:239], v[172:175], v[50:53]
	v_mfma_f32_16x16x32_bf16 v[38:41], v[228:231], v[180:183], v[38:41]
	v_mfma_f32_16x16x32_bf16 v[34:37], v[236:239], v[180:183], v[34:37]
	v_mfma_f32_16x16x32_bf16 v[22:25], v[228:231], v[188:191], v[22:25]
	v_mfma_f32_16x16x32_bf16 v[18:21], v[236:239], v[188:191], v[18:21]
	v_mfma_f32_16x16x32_bf16 v[6:9], v[228:231], v[196:199], v[6:9]
	v_mfma_f32_16x16x32_bf16 v[2:5], v[236:239], v[196:199], v[2:5]
	s_barrier
	s_add_u32 s0, s0, 0x100
	s_addc_u32 s1, s1, 0
	s_add_u32 s13, s13, 0x100
	s_addc_u32 s66, s66, 0
	s_mov_b32 s50, s67
	s_cmp_ge_i32 s67, s41
	s_cbranch_scc0 .LBB0_282
	s_cmp_eq_u32 s63, 2
	s_cbranch_scc1 .Lepi6_orig
	v_readlane_b32 s90, v255, 17
	v_readlane_b32 s91, v255, 18
	v_readlane_b32 s96, v255, 19
	v_readlane_b32 s97, v255, 20
	v_readlane_b32 s8, v255, 25
	v_readlane_b32 s9, v255, 26
	v_readlane_b32 s68, v253, 58
	v_readlane_b32 s69, v253, 59
	v_lshl_or_b32 v156, s64, 8, v154
	v_lshlrev_b32_e32 v156, 2, v156
	v_lshl_add_u32 v157, v152, 13, v156
	s_lshl_b32 s72, s65, 21
	s_add_u32 s74, s68, s72
	s_addc_u32 s75, s69, 0
	s_add_u32 s76, s22, s72
	s_addc_u32 s77, s23, 0
	s_lshr_b32 s73, s65, 3
	s_mul_i32 s73, s73, 0xc000
	s_add_u32 s73, s73, 0x4000
	s_add_u32 s70, s90, s73
	s_addc_u32 s71, s91, 0
	global_load_dwordx4 v[140:143], v156, s[70:71]
	global_load_dwordx4 v[144:147], v156, s[70:71] offset:64
	global_load_dwordx4 v[148:151], v156, s[70:71] offset:512
	global_load_dwordx4 v[168:171], v156, s[70:71] offset:576
	global_load_dwordx4 v[224:227], v157, s[74:75] nt
	global_load_dwordx4 v[228:231], v157, s[74:75] offset:64 nt
	global_load_dwordx4 v[232:235], v157, s[74:75] offset:512 nt
	global_load_dwordx4 v[236:239], v157, s[74:75] offset:576 nt
	s_add_u32 s74, s74, 0x20000
	s_addc_u32 s75, s75, 0
	global_load_dwordx4 v[240:243], v157, s[74:75] nt
	global_load_dwordx4 v[244:247], v157, s[74:75] offset:64 nt
	s_waitcnt vmcnt(5)
	v_pk_fma_f32 v[128:129], v[128:129], v[142:143], v[226:227]
	v_pk_fma_f32 v[126:127], v[126:127], v[140:141], v[224:225]
	global_store_dwordx4 v157, v[126:129], s[76:77]
	global_load_dwordx4 v[224:227], v157, s[74:75] offset:512 nt
	s_waitcnt vmcnt(6)
	v_pk_fma_f32 v[124:125], v[124:125], v[146:147], v[230:231]
	v_pk_fma_f32 v[122:123], v[122:123], v[144:145], v[228:229]
	global_store_dwordx4 v157, v[122:125], s[76:77] offset:64
	global_load_dwordx4 v[228:231], v157, s[74:75] offset:576 nt
	s_waitcnt vmcnt(7)
	v_pk_fma_f32 v[120:121], v[120:121], v[150:151], v[234:235]
	v_pk_fma_f32 v[118:119], v[118:119], v[148:149], v[232:233]
	global_store_dwordx4 v157, v[118:121], s[76:77] offset:512
	s_add_u32 s74, s74, 0x20000
	s_addc_u32 s75, s75, 0
	global_load_dwordx4 v[232:235], v157, s[74:75] nt
	s_waitcnt vmcnt(8)
	v_pk_fma_f32 v[116:117], v[116:117], v[170:171], v[238:239]
	v_pk_fma_f32 v[114:115], v[114:115], v[168:169], v[236:237]
	global_store_dwordx4 v157, v[114:117], s[76:77] offset:576
	global_load_dwordx4 v[236:239], v157, s[74:75] offset:64 nt
	s_add_u32 s76, s76, 0x20000
	s_addc_u32 s77, s77, 0
	s_waitcnt vmcnt(9)
	v_pk_fma_f32 v[112:113], v[112:113], v[142:143], v[242:243]
	v_pk_fma_f32 v[110:111], v[110:111], v[140:141], v[240:241]
	global_store_dwordx4 v157, v[110:113], s[76:77]
	global_load_dwordx4 v[240:243], v157, s[74:75] offset:512 nt
	s_waitcnt vmcnt(10)
	v_pk_fma_f32 v[108:109], v[108:109], v[146:147], v[246:247]
	v_pk_fma_f32 v[106:107], v[106:107], v[144:145], v[244:245]
	global_store_dwordx4 v157, v[106:109], s[76:77] offset:64
	global_load_dwordx4 v[244:247], v157, s[74:75] offset:576 nt
	s_waitcnt vmcnt(10)
	v_pk_fma_f32 v[104:105], v[104:105], v[150:151], v[226:227]
	v_pk_fma_f32 v[102:103], v[102:103], v[148:149], v[224:225]
	global_store_dwordx4 v157, v[102:105], s[76:77] offset:512
	s_add_u32 s74, s74, 0x20000
	s_addc_u32 s75, s75, 0
	global_load_dwordx4 v[224:227], v157, s[74:75] nt
	s_waitcnt vmcnt(10)
	v_pk_fma_f32 v[100:101], v[100:101], v[170:171], v[230:231]
	v_pk_fma_f32 v[98:99], v[98:99], v[168:169], v[228:229]
	global_store_dwordx4 v157, v[98:101], s[76:77] offset:576
	global_load_dwordx4 v[228:231], v157, s[74:75] offset:64 nt
	s_add_u32 s76, s76, 0x20000
	s_addc_u32 s77, s77, 0
	s_waitcnt vmcnt(10)
	v_pk_fma_f32 v[96:97], v[96:97], v[142:143], v[234:235]
	v_pk_fma_f32 v[94:95], v[94:95], v[140:141], v[232:233]
	global_store_dwordx4 v157, v[94:97], s[76:77]
	global_load_dwordx4 v[232:235], v157, s[74:75] offset:512 nt
	s_waitcnt vmcnt(10)
	v_pk_fma_f32 v[92:93], v[92:93], v[146:147], v[238:239]
	v_pk_fma_f32 v[90:91], v[90:91], v[144:145], v[236:237]
	global_store_dwordx4 v157, v[90:93], s[76:77] offset:64
	global_load_dwordx4 v[236:239], v157, s[74:75] offset:576 nt
	s_waitcnt vmcnt(10)
	v_pk_fma_f32 v[88:89], v[88:89], v[150:151], v[242:243]
	v_pk_fma_f32 v[86:87], v[86:87], v[148:149], v[240:241]
	global_store_dwordx4 v157, v[86:89], s[76:77] offset:512
	s_add_u32 s74, s74, 0xa0000
	s_addc_u32 s75, s75, 0
	global_load_dwordx4 v[240:243], v157, s[74:75] nt
	s_waitcnt vmcnt(10)
	v_pk_fma_f32 v[84:85], v[84:85], v[170:171], v[246:247]
	v_pk_fma_f32 v[82:83], v[82:83], v[168:169], v[244:245]
	global_store_dwordx4 v157, v[82:85], s[76:77] offset:576
	global_load_dwordx4 v[244:247], v157, s[74:75] offset:64 nt
	s_add_u32 s76, s76, 0x20000
	s_addc_u32 s77, s77, 0
	s_waitcnt vmcnt(10)
	v_pk_fma_f32 v[80:81], v[80:81], v[142:143], v[226:227]
	v_pk_fma_f32 v[78:79], v[78:79], v[140:141], v[224:225]
	global_store_dwordx4 v157, v[78:81], s[76:77]
	global_load_dwordx4 v[224:227], v157, s[74:75] offset:512 nt
	s_waitcnt vmcnt(10)
	v_pk_fma_f32 v[76:77], v[76:77], v[146:147], v[230:231]
	v_pk_fma_f32 v[74:75], v[74:75], v[144:145], v[228:229]
	global_store_dwordx4 v157, v[74:77], s[76:77] offset:64
	global_load_dwordx4 v[228:231], v157, s[74:75] offset:576 nt
	s_waitcnt vmcnt(10)
	v_pk_fma_f32 v[72:73], v[72:73], v[150:151], v[234:235]
	v_pk_fma_f32 v[70:71], v[70:71], v[148:149], v[232:233]
	global_store_dwordx4 v157, v[70:73], s[76:77] offset:512
	s_add_u32 s74, s74, 0x20000
	s_addc_u32 s75, s75, 0
	global_load_dwordx4 v[232:235], v157, s[74:75] nt
	s_waitcnt vmcnt(10)
	v_pk_fma_f32 v[68:69], v[68:69], v[170:171], v[238:239]
	v_pk_fma_f32 v[66:67], v[66:67], v[168:169], v[236:237]
	global_store_dwordx4 v157, v[66:69], s[76:77] offset:576
	global_load_dwordx4 v[236:239], v157, s[74:75] offset:64 nt
	s_add_u32 s76, s76, 0xa0000
	s_addc_u32 s77, s77, 0
	s_waitcnt vmcnt(10)
	v_pk_fma_f32 v[64:65], v[64:65], v[142:143], v[242:243]
	v_pk_fma_f32 v[62:63], v[62:63], v[140:141], v[240:241]
	global_store_dwordx4 v157, v[62:65], s[76:77]
	global_load_dwordx4 v[240:243], v157, s[74:75] offset:512 nt
	s_waitcnt vmcnt(10)
	v_pk_fma_f32 v[60:61], v[60:61], v[146:147], v[246:247]
	v_pk_fma_f32 v[58:59], v[58:59], v[144:145], v[244:245]
	global_store_dwordx4 v157, v[58:61], s[76:77] offset:64
	global_load_dwordx4 v[244:247], v157, s[74:75] offset:576 nt
	s_waitcnt vmcnt(10)
	v_pk_fma_f32 v[56:57], v[56:57], v[150:151], v[226:227]
	v_pk_fma_f32 v[54:55], v[54:55], v[148:149], v[224:225]
	global_store_dwordx4 v157, v[54:57], s[76:77] offset:512
	s_add_u32 s74, s74, 0x20000
	s_addc_u32 s75, s75, 0
	global_load_dwordx4 v[224:227], v157, s[74:75] nt
	s_waitcnt vmcnt(10)
	v_pk_fma_f32 v[52:53], v[52:53], v[170:171], v[230:231]
	v_pk_fma_f32 v[50:51], v[50:51], v[168:169], v[228:229]
	global_store_dwordx4 v157, v[50:53], s[76:77] offset:576
	global_load_dwordx4 v[228:231], v157, s[74:75] offset:64 nt
	s_add_u32 s76, s76, 0x20000
	s_addc_u32 s77, s77, 0
	s_waitcnt vmcnt(10)
	v_pk_fma_f32 v[48:49], v[48:49], v[142:143], v[234:235]
	v_pk_fma_f32 v[46:47], v[46:47], v[140:141], v[232:233]
	global_store_dwordx4 v157, v[46:49], s[76:77]
	global_load_dwordx4 v[232:235], v157, s[74:75] offset:512 nt
	s_waitcnt vmcnt(10)
	v_pk_fma_f32 v[44:45], v[44:45], v[146:147], v[238:239]
	v_pk_fma_f32 v[42:43], v[42:43], v[144:145], v[236:237]
	global_store_dwordx4 v157, v[42:45], s[76:77] offset:64
	global_load_dwordx4 v[236:239], v157, s[74:75] offset:576 nt
	s_waitcnt vmcnt(10)
	v_pk_fma_f32 v[40:41], v[40:41], v[150:151], v[242:243]
	v_pk_fma_f32 v[38:39], v[38:39], v[148:149], v[240:241]
	global_store_dwordx4 v157, v[38:41], s[76:77] offset:512
	s_add_u32 s74, s74, 0x20000
	s_addc_u32 s75, s75, 0
	global_load_dwordx4 v[240:243], v157, s[74:75] nt
	s_waitcnt vmcnt(10)
	v_pk_fma_f32 v[36:37], v[36:37], v[170:171], v[246:247]
	v_pk_fma_f32 v[34:35], v[34:35], v[168:169], v[244:245]
	global_store_dwordx4 v157, v[34:37], s[76:77] offset:576
	global_load_dwordx4 v[244:247], v157, s[74:75] offset:64 nt
	s_add_u32 s76, s76, 0x20000
	s_addc_u32 s77, s77, 0
	s_waitcnt vmcnt(10)
	v_pk_fma_f32 v[32:33], v[32:33], v[142:143], v[226:227]
	v_pk_fma_f32 v[30:31], v[30:31], v[140:141], v[224:225]
	global_store_dwordx4 v157, v[30:33], s[76:77]
	global_load_dwordx4 v[224:227], v157, s[74:75] offset:512 nt
	s_waitcnt vmcnt(10)
	v_pk_fma_f32 v[28:29], v[28:29], v[146:147], v[230:231]
	v_pk_fma_f32 v[26:27], v[26:27], v[144:145], v[228:229]
	global_store_dwordx4 v157, v[26:29], s[76:77] offset:64
	global_load_dwordx4 v[228:231], v157, s[74:75] offset:576 nt
	s_waitcnt vmcnt(10)
	v_pk_fma_f32 v[24:25], v[24:25], v[150:151], v[234:235]
	v_pk_fma_f32 v[22:23], v[22:23], v[148:149], v[232:233]
	global_store_dwordx4 v157, v[22:25], s[76:77] offset:512
	s_waitcnt vmcnt(9)
	v_pk_fma_f32 v[20:21], v[20:21], v[170:171], v[238:239]
	v_pk_fma_f32 v[18:19], v[18:19], v[168:169], v[236:237]
	global_store_dwordx4 v157, v[18:21], s[76:77] offset:576
	s_add_u32 s76, s76, 0x20000
	s_addc_u32 s77, s77, 0
	s_waitcnt vmcnt(8)
	v_pk_fma_f32 v[16:17], v[16:17], v[142:143], v[242:243]
	v_pk_fma_f32 v[14:15], v[14:15], v[140:141], v[240:241]
	global_store_dwordx4 v157, v[14:17], s[76:77]
	s_waitcnt vmcnt(7)
	v_pk_fma_f32 v[12:13], v[12:13], v[146:147], v[246:247]
	v_pk_fma_f32 v[10:11], v[10:11], v[144:145], v[244:245]
	global_store_dwordx4 v157, v[10:13], s[76:77] offset:64
	s_waitcnt vmcnt(6)
	v_pk_fma_f32 v[8:9], v[8:9], v[150:151], v[226:227]
	v_pk_fma_f32 v[6:7], v[6:7], v[148:149], v[224:225]
	global_store_dwordx4 v157, v[6:9], s[76:77] offset:512
	s_waitcnt vmcnt(5)
	v_pk_fma_f32 v[4:5], v[4:5], v[170:171], v[230:231]
	v_pk_fma_f32 v[2:3], v[2:3], v[168:169], v[228:229]
	global_store_dwordx4 v157, v[2:5], s[76:77] offset:576
	s_branch .LBB0_269

.LBB0_572:
	s_add_u32 s41, s46, 0xfff80080
	s_addc_u32 s48, s47, -1
	s_add_i32 s64, 0, 0x10000
	ds_read_b128 v[144:147], v141
	ds_read_b128 v[148:151], v141 offset:1024
	ds_read_b128 v[152:155], v141 offset:2048
	ds_read_b128 v[168:171], v141 offset:3072
	s_cmp_eq_u32 s39, 28
	s_cselect_b32 s51, s43, s48
	s_cselect_b32 s50, s42, s41
	s_cselect_b32 s49, s45, s13
	s_cselect_b32 s48, s44, s12
	ds_read_b128 v[172:175], v143
	ds_read_b128 v[176:179], v143 offset:1024
	ds_read_b128 v[180:183], v143 offset:2048
	ds_read_b128 v[184:187], v143 offset:3072
	ds_read_b128 v[188:191], v143 offset:4096
	ds_read_b128 v[192:195], v143 offset:5120
	ds_read_b128 v[196:199], v143 offset:6144
	ds_read_b128 v[224:227], v143 offset:7168
	s_add_i32 m0, s54, 0xc000
	s_nop 0
	global_load_lds_dwordx4 v136, s[46:47]
	s_add_i32 m0, s54, 0xe000
	s_nop 0
	global_load_lds_dwordx4 v138, s[46:47]
	s_add_i32 s41, 0, 0x14000
	s_add_i32 s64, s64, s53
	ds_read_b128 v[228:231], v141 offset:16384
	ds_read_b128 v[232:235], v141 offset:17408
	ds_read_b128 v[236:239], v141 offset:18432
	ds_read_b128 v[240:243], v141 offset:19456
	s_waitcnt lgkmcnt(0)
	s_barrier
	v_mfma_f32_16x16x32_bf16 v[126:129], v[144:147], v[172:175], v[126:129]
	v_mfma_f32_16x16x32_bf16 v[122:125], v[152:155], v[172:175], v[122:125]
	v_mfma_f32_16x16x32_bf16 v[118:121], v[144:147], v[180:183], v[118:121]
	v_mfma_f32_16x16x32_bf16 v[114:117], v[152:155], v[180:183], v[114:117]
	v_mfma_f32_16x16x32_bf16 v[102:105], v[144:147], v[188:191], v[102:105]
	v_mfma_f32_16x16x32_bf16 v[98:101], v[152:155], v[188:191], v[98:101]
	v_mfma_f32_16x16x32_bf16 v[86:89], v[144:147], v[196:199], v[86:89]
	v_mfma_f32_16x16x32_bf16 v[82:85], v[152:155], v[196:199], v[82:85]
	v_mfma_f32_16x16x32_bf16 v[126:129], v[148:151], v[176:179], v[126:129]
	v_mfma_f32_16x16x32_bf16 v[122:125], v[168:171], v[176:179], v[122:125]
	v_mfma_f32_16x16x32_bf16 v[118:121], v[148:151], v[184:187], v[118:121]
	v_mfma_f32_16x16x32_bf16 v[114:117], v[168:171], v[184:187], v[114:117]
	v_mfma_f32_16x16x32_bf16 v[102:105], v[148:151], v[192:195], v[102:105]
	v_mfma_f32_16x16x32_bf16 v[98:101], v[168:171], v[192:195], v[98:101]
	v_mfma_f32_16x16x32_bf16 v[86:89], v[148:151], v[224:227], v[86:89]
	v_mfma_f32_16x16x32_bf16 v[82:85], v[168:171], v[224:227], v[82:85]
	v_mfma_f32_16x16x32_bf16 v[110:113], v[228:231], v[172:175], v[110:113]
	v_mfma_f32_16x16x32_bf16 v[106:109], v[236:239], v[172:175], v[106:109]
	v_mfma_f32_16x16x32_bf16 v[94:97], v[228:231], v[180:183], v[94:97]
	v_mfma_f32_16x16x32_bf16 v[90:93], v[236:239], v[180:183], v[90:93]
	v_mfma_f32_16x16x32_bf16 v[78:81], v[228:231], v[188:191], v[78:81]
	v_mfma_f32_16x16x32_bf16 v[74:77], v[236:239], v[188:191], v[74:77]
	v_mfma_f32_16x16x32_bf16 v[70:73], v[228:231], v[196:199], v[70:73]
	v_mfma_f32_16x16x32_bf16 v[66:69], v[236:239], v[196:199], v[66:69]
	v_mfma_f32_16x16x32_bf16 v[110:113], v[232:235], v[176:179], v[110:113]
	v_mfma_f32_16x16x32_bf16 v[106:109], v[240:243], v[176:179], v[106:109]
	v_mfma_f32_16x16x32_bf16 v[94:97], v[232:235], v[184:187], v[94:97]
	v_mfma_f32_16x16x32_bf16 v[90:93], v[240:243], v[184:187], v[90:93]
	v_mfma_f32_16x16x32_bf16 v[78:81], v[232:235], v[192:195], v[78:81]
	v_mfma_f32_16x16x32_bf16 v[74:77], v[240:243], v[192:195], v[74:77]
	v_mfma_f32_16x16x32_bf16 v[70:73], v[232:235], v[224:227], v[70:73]
	v_mfma_f32_16x16x32_bf16 v[66:69], v[240:243], v[224:227], v[66:69]
	s_barrier
	s_mov_b32 m0, s54
	s_add_u32 s78, s50, s94
	s_addc_u32 s79, s51, s95
	ds_read_b128 v[172:175], v143 offset:16384
	ds_read_b128 v[176:179], v143 offset:17408
	ds_read_b128 v[180:183], v143 offset:18432
	ds_read_b128 v[184:187], v143 offset:19456
	ds_read_b128 v[188:191], v143 offset:20480
	ds_read_b128 v[192:195], v143 offset:21504
	ds_read_b128 v[196:199], v143 offset:22528
	ds_read_b128 v[224:227], v143 offset:23552
	global_load_lds_dwordx4 v130, s[50:51]
	s_mov_b32 m0, s55
	s_nop 0
	global_load_lds_dwordx4 v132, s[50:51]
	s_add_u32 s76, s48, s94
	s_addc_u32 s77, s49, s95
	s_mov_b32 m0, s64
	s_nop 0
	global_load_lds_dwordx4 v0, s[48:49]
	s_add_i32 m0, s64, 0x2000
	s_nop 0
	global_load_lds_dwordx4 v134, s[48:49]
	s_add_u32 s64, s48, 0x80000
	s_addc_u32 s65, s49, 0
	s_add_i32 s41, s41, s53
	s_mov_b32 m0, s41
	s_nop 0
	global_load_lds_dwordx4 v0, s[64:65]
	s_add_i32 m0, s41, 0x2000
	s_nop 0
	global_load_lds_dwordx4 v134, s[64:65]
	s_waitcnt vmcnt(6) lgkmcnt(0)
	s_barrier
	v_mfma_f32_16x16x32_bf16 v[62:65], v[144:147], v[172:175], v[62:65]
	v_mfma_f32_16x16x32_bf16 v[58:61], v[152:155], v[172:175], v[58:61]
	v_mfma_f32_16x16x32_bf16 v[54:57], v[144:147], v[180:183], v[54:57]
	v_mfma_f32_16x16x32_bf16 v[50:53], v[152:155], v[180:183], v[50:53]
	v_mfma_f32_16x16x32_bf16 v[38:41], v[144:147], v[188:191], v[38:41]
	v_mfma_f32_16x16x32_bf16 v[34:37], v[152:155], v[188:191], v[34:37]
	v_mfma_f32_16x16x32_bf16 v[22:25], v[144:147], v[196:199], v[22:25]
	v_mfma_f32_16x16x32_bf16 v[18:21], v[152:155], v[196:199], v[18:21]
	v_mfma_f32_16x16x32_bf16 v[62:65], v[148:151], v[176:179], v[62:65]
	v_mfma_f32_16x16x32_bf16 v[58:61], v[168:171], v[176:179], v[58:61]
	v_mfma_f32_16x16x32_bf16 v[54:57], v[148:151], v[184:187], v[54:57]
	v_mfma_f32_16x16x32_bf16 v[50:53], v[168:171], v[184:187], v[50:53]
	v_mfma_f32_16x16x32_bf16 v[38:41], v[148:151], v[192:195], v[38:41]
	v_mfma_f32_16x16x32_bf16 v[34:37], v[168:171], v[192:195], v[34:37]
	v_mfma_f32_16x16x32_bf16 v[22:25], v[148:151], v[224:227], v[22:25]
	v_mfma_f32_16x16x32_bf16 v[18:21], v[168:171], v[224:227], v[18:21]
	v_mfma_f32_16x16x32_bf16 v[46:49], v[228:231], v[172:175], v[46:49]
	v_mfma_f32_16x16x32_bf16 v[42:45], v[236:239], v[172:175], v[42:45]
	v_mfma_f32_16x16x32_bf16 v[30:33], v[228:231], v[180:183], v[30:33]
	v_mfma_f32_16x16x32_bf16 v[26:29], v[236:239], v[180:183], v[26:29]
	v_mfma_f32_16x16x32_bf16 v[14:17], v[228:231], v[188:191], v[14:17]
	v_mfma_f32_16x16x32_bf16 v[10:13], v[236:239], v[188:191], v[10:13]
	v_mfma_f32_16x16x32_bf16 v[6:9], v[228:231], v[196:199], v[6:9]
	v_mfma_f32_16x16x32_bf16 v[2:5], v[236:239], v[196:199], v[2:5]
	v_mfma_f32_16x16x32_bf16 v[46:49], v[232:235], v[176:179], v[46:49]
	v_mfma_f32_16x16x32_bf16 v[42:45], v[240:243], v[176:179], v[42:45]
	v_mfma_f32_16x16x32_bf16 v[30:33], v[232:235], v[184:187], v[30:33]
	v_mfma_f32_16x16x32_bf16 v[26:29], v[240:243], v[184:187], v[26:29]
	v_mfma_f32_16x16x32_bf16 v[14:17], v[232:235], v[192:195], v[14:17]
	v_mfma_f32_16x16x32_bf16 v[10:13], v[240:243], v[192:195], v[10:13]
	v_mfma_f32_16x16x32_bf16 v[6:9], v[232:235], v[224:227], v[6:9]
	v_mfma_f32_16x16x32_bf16 v[2:5], v[240:243], v[224:227], v[2:5]
	s_barrier
	s_add_i32 s41, 0, 0x18000
	ds_read_b128 v[144:147], v141 offset:32768
	ds_read_b128 v[148:151], v141 offset:33792
	ds_read_b128 v[152:155], v141 offset:34816
	ds_read_b128 v[168:171], v141 offset:35840
	s_add_u32 s50, s50, 0x80000
	s_addc_u32 s51, s51, 0
	ds_read_b128 v[172:175], v143 offset:32768
	ds_read_b128 v[176:179], v143 offset:33792
	ds_read_b128 v[180:183], v143 offset:34816
	ds_read_b128 v[184:187], v143 offset:35840
	ds_read_b128 v[188:191], v143 offset:36864
	ds_read_b128 v[192:195], v143 offset:37888
	ds_read_b128 v[196:199], v143 offset:38912
	ds_read_b128 v[224:227], v143 offset:39936
	s_mov_b32 m0, s56
	s_nop 0
	global_load_lds_dwordx4 v130, s[50:51]
	s_mov_b32 m0, s57
	s_nop 0
	global_load_lds_dwordx4 v132, s[50:51]
	s_add_i32 s50, 0, 0x1c000
	s_add_i32 s41, s41, s53
	ds_read_b128 v[228:231], v141 offset:49152
	ds_read_b128 v[232:235], v141 offset:50176
	ds_read_b128 v[236:239], v141 offset:51200
	ds_read_b128 v[240:243], v141 offset:52224
	s_waitcnt lgkmcnt(0)
	s_barrier
	v_mfma_f32_16x16x32_bf16 v[126:129], v[144:147], v[172:175], v[126:129]
	v_mfma_f32_16x16x32_bf16 v[122:125], v[152:155], v[172:175], v[122:125]
	v_mfma_f32_16x16x32_bf16 v[118:121], v[144:147], v[180:183], v[118:121]
	v_mfma_f32_16x16x32_bf16 v[114:117], v[152:155], v[180:183], v[114:117]
	v_mfma_f32_16x16x32_bf16 v[102:105], v[144:147], v[188:191], v[102:105]
	v_mfma_f32_16x16x32_bf16 v[98:101], v[152:155], v[188:191], v[98:101]
	v_mfma_f32_16x16x32_bf16 v[86:89], v[144:147], v[196:199], v[86:89]
	v_mfma_f32_16x16x32_bf16 v[82:85], v[152:155], v[196:199], v[82:85]
	v_mfma_f32_16x16x32_bf16 v[126:129], v[148:151], v[176:179], v[126:129]
	v_mfma_f32_16x16x32_bf16 v[122:125], v[168:171], v[176:179], v[122:125]
	v_mfma_f32_16x16x32_bf16 v[118:121], v[148:151], v[184:187], v[118:121]
	v_mfma_f32_16x16x32_bf16 v[114:117], v[168:171], v[184:187], v[114:117]
	v_mfma_f32_16x16x32_bf16 v[102:105], v[148:151], v[192:195], v[102:105]
	v_mfma_f32_16x16x32_bf16 v[98:101], v[168:171], v[192:195], v[98:101]
	v_mfma_f32_16x16x32_bf16 v[86:89], v[148:151], v[224:227], v[86:89]
	v_mfma_f32_16x16x32_bf16 v[82:85], v[168:171], v[224:227], v[82:85]
	v_mfma_f32_16x16x32_bf16 v[110:113], v[228:231], v[172:175], v[110:113]
	v_mfma_f32_16x16x32_bf16 v[106:109], v[236:239], v[172:175], v[106:109]
	v_mfma_f32_16x16x32_bf16 v[94:97], v[228:231], v[180:183], v[94:97]
	v_mfma_f32_16x16x32_bf16 v[90:93], v[236:239], v[180:183], v[90:93]
	v_mfma_f32_16x16x32_bf16 v[78:81], v[228:231], v[188:191], v[78:81]
	v_mfma_f32_16x16x32_bf16 v[74:77], v[236:239], v[188:191], v[74:77]
	v_mfma_f32_16x16x32_bf16 v[70:73], v[228:231], v[196:199], v[70:73]
	v_mfma_f32_16x16x32_bf16 v[66:69], v[236:239], v[196:199], v[66:69]
	v_mfma_f32_16x16x32_bf16 v[110:113], v[232:235], v[176:179], v[110:113]
	v_mfma_f32_16x16x32_bf16 v[106:109], v[240:243], v[176:179], v[106:109]
	v_mfma_f32_16x16x32_bf16 v[94:97], v[232:235], v[184:187], v[94:97]
	v_mfma_f32_16x16x32_bf16 v[90:93], v[240:243], v[184:187], v[90:93]
	v_mfma_f32_16x16x32_bf16 v[78:81], v[232:235], v[192:195], v[78:81]
	v_mfma_f32_16x16x32_bf16 v[74:77], v[240:243], v[192:195], v[74:77]
	v_mfma_f32_16x16x32_bf16 v[70:73], v[232:235], v[224:227], v[70:73]
	v_mfma_f32_16x16x32_bf16 v[66:69], v[240:243], v[224:227], v[66:69]
	s_barrier
	s_mov_b32 m0, s59
	ds_read_b128 v[172:175], v143 offset:49152
	ds_read_b128 v[176:179], v143 offset:50176
	ds_read_b128 v[180:183], v143 offset:51200
	ds_read_b128 v[184:187], v143 offset:52224
	ds_read_b128 v[188:191], v143 offset:53248
	ds_read_b128 v[192:195], v143 offset:54272
	ds_read_b128 v[196:199], v143 offset:55296
	ds_read_b128 v[224:227], v143 offset:56320
	global_load_lds_dwordx4 v130, s[78:79]
	s_mov_b32 m0, s60
	s_nop 0
	global_load_lds_dwordx4 v132, s[78:79]
	s_mov_b32 m0, s41
	s_nop 0
	global_load_lds_dwordx4 v0, s[76:77]
	s_add_i32 m0, s41, 0x2000
	s_nop 0
	global_load_lds_dwordx4 v134, s[76:77]
	s_add_u32 s48, s48, 0x80080
	s_addc_u32 s49, s49, 0
	s_add_i32 s41, s50, s53
	s_mov_b32 m0, s41
	s_nop 0
	global_load_lds_dwordx4 v0, s[48:49]
	s_add_i32 m0, s41, 0x2000
	s_nop 0
	global_load_lds_dwordx4 v134, s[48:49]
	s_waitcnt vmcnt(6) lgkmcnt(0)
	s_barrier
	v_mfma_f32_16x16x32_bf16 v[62:65], v[144:147], v[172:175], v[62:65]
	v_mfma_f32_16x16x32_bf16 v[58:61], v[152:155], v[172:175], v[58:61]
	v_mfma_f32_16x16x32_bf16 v[54:57], v[144:147], v[180:183], v[54:57]
	v_mfma_f32_16x16x32_bf16 v[50:53], v[152:155], v[180:183], v[50:53]
	v_mfma_f32_16x16x32_bf16 v[38:41], v[144:147], v[188:191], v[38:41]
	v_mfma_f32_16x16x32_bf16 v[34:37], v[152:155], v[188:191], v[34:37]
	v_mfma_f32_16x16x32_bf16 v[22:25], v[144:147], v[196:199], v[22:25]
	v_mfma_f32_16x16x32_bf16 v[18:21], v[152:155], v[196:199], v[18:21]
	v_mfma_f32_16x16x32_bf16 v[62:65], v[148:151], v[176:179], v[62:65]
	v_mfma_f32_16x16x32_bf16 v[58:61], v[168:171], v[176:179], v[58:61]
	v_mfma_f32_16x16x32_bf16 v[54:57], v[148:151], v[184:187], v[54:57]
	v_mfma_f32_16x16x32_bf16 v[50:53], v[168:171], v[184:187], v[50:53]
	v_mfma_f32_16x16x32_bf16 v[38:41], v[148:151], v[192:195], v[38:41]
	v_mfma_f32_16x16x32_bf16 v[34:37], v[168:171], v[192:195], v[34:37]
	v_mfma_f32_16x16x32_bf16 v[22:25], v[148:151], v[224:227], v[22:25]
	v_mfma_f32_16x16x32_bf16 v[18:21], v[168:171], v[224:227], v[18:21]
	v_mfma_f32_16x16x32_bf16 v[46:49], v[228:231], v[172:175], v[46:49]
	v_mfma_f32_16x16x32_bf16 v[42:45], v[236:239], v[172:175], v[42:45]
	v_mfma_f32_16x16x32_bf16 v[30:33], v[228:231], v[180:183], v[30:33]
	v_mfma_f32_16x16x32_bf16 v[26:29], v[236:239], v[180:183], v[26:29]
	v_mfma_f32_16x16x32_bf16 v[14:17], v[228:231], v[188:191], v[14:17]
	v_mfma_f32_16x16x32_bf16 v[10:13], v[236:239], v[188:191], v[10:13]
	v_mfma_f32_16x16x32_bf16 v[6:9], v[228:231], v[196:199], v[6:9]
	v_mfma_f32_16x16x32_bf16 v[2:5], v[236:239], v[196:199], v[2:5]
	v_mfma_f32_16x16x32_bf16 v[46:49], v[232:235], v[176:179], v[46:49]
	v_mfma_f32_16x16x32_bf16 v[42:45], v[240:243], v[176:179], v[42:45]
	v_mfma_f32_16x16x32_bf16 v[30:33], v[232:235], v[184:187], v[30:33]
	v_mfma_f32_16x16x32_bf16 v[26:29], v[240:243], v[184:187], v[26:29]
	v_mfma_f32_16x16x32_bf16 v[14:17], v[232:235], v[192:195], v[14:17]
	v_mfma_f32_16x16x32_bf16 v[10:13], v[240:243], v[192:195], v[10:13]
	v_mfma_f32_16x16x32_bf16 v[6:9], v[232:235], v[224:227], v[6:9]
	v_mfma_f32_16x16x32_bf16 v[2:5], v[240:243], v[224:227], v[2:5]
	s_barrier
	s_add_i32 s39, s39, 2
	s_add_u32 s46, s46, 0x100
	s_addc_u32 s47, s47, 0
	s_add_u32 s12, s12, 0x100
	s_addc_u32 s13, s13, 0
	s_cmp_gt_u32 s39, 29
	s_cbranch_scc0 .LBB0_572
	s_cmp_lg_u32 s62, 0
	s_cbranch_scc0 .LBB0_575
	s_lshl_b32 s39, s61, 8
	s_mov_b64 s[12:13], 0
	s_branch .LBB0_576

.LBB0_788:
	s_add_u32 s39, s46, 0xfff80080
	s_addc_u32 s48, s47, -1
	s_add_i32 s64, 0, 0x10000
	ds_read_b128 v[144:147], v141
	ds_read_b128 v[148:151], v141 offset:1024
	ds_read_b128 v[152:155], v141 offset:2048
	ds_read_b128 v[168:171], v141 offset:3072
	s_cmp_eq_u32 s13, 28
	s_cselect_b32 s51, s43, s48
	s_cselect_b32 s50, s42, s39
	s_cselect_b32 s49, s45, s12
	s_cselect_b32 s48, s44, s1
	ds_read_b128 v[172:175], v143
	ds_read_b128 v[176:179], v143 offset:1024
	ds_read_b128 v[180:183], v143 offset:2048
	ds_read_b128 v[184:187], v143 offset:3072
	ds_read_b128 v[188:191], v143 offset:4096
	ds_read_b128 v[192:195], v143 offset:5120
	ds_read_b128 v[196:199], v143 offset:6144
	ds_read_b128 v[224:227], v143 offset:7168
	s_add_i32 m0, s54, 0xc000
	s_nop 0
	global_load_lds_dwordx4 v136, s[46:47]
	s_add_i32 m0, s54, 0xe000
	s_nop 0
	global_load_lds_dwordx4 v138, s[46:47]
	s_add_i32 s39, 0, 0x14000
	s_add_i32 s64, s64, s53
	ds_read_b128 v[228:231], v141 offset:16384
	ds_read_b128 v[232:235], v141 offset:17408
	ds_read_b128 v[236:239], v141 offset:18432
	ds_read_b128 v[240:243], v141 offset:19456
	s_waitcnt lgkmcnt(0)
	s_barrier
	v_mfma_f32_16x16x32_bf16 v[126:129], v[144:147], v[172:175], v[126:129]
	v_mfma_f32_16x16x32_bf16 v[122:125], v[152:155], v[172:175], v[122:125]
	v_mfma_f32_16x16x32_bf16 v[118:121], v[144:147], v[180:183], v[118:121]
	v_mfma_f32_16x16x32_bf16 v[114:117], v[152:155], v[180:183], v[114:117]
	v_mfma_f32_16x16x32_bf16 v[102:105], v[144:147], v[188:191], v[102:105]
	v_mfma_f32_16x16x32_bf16 v[98:101], v[152:155], v[188:191], v[98:101]
	v_mfma_f32_16x16x32_bf16 v[86:89], v[144:147], v[196:199], v[86:89]
	v_mfma_f32_16x16x32_bf16 v[82:85], v[152:155], v[196:199], v[82:85]
	v_mfma_f32_16x16x32_bf16 v[126:129], v[148:151], v[176:179], v[126:129]
	v_mfma_f32_16x16x32_bf16 v[122:125], v[168:171], v[176:179], v[122:125]
	v_mfma_f32_16x16x32_bf16 v[118:121], v[148:151], v[184:187], v[118:121]
	v_mfma_f32_16x16x32_bf16 v[114:117], v[168:171], v[184:187], v[114:117]
	v_mfma_f32_16x16x32_bf16 v[102:105], v[148:151], v[192:195], v[102:105]
	v_mfma_f32_16x16x32_bf16 v[98:101], v[168:171], v[192:195], v[98:101]
	v_mfma_f32_16x16x32_bf16 v[86:89], v[148:151], v[224:227], v[86:89]
	v_mfma_f32_16x16x32_bf16 v[82:85], v[168:171], v[224:227], v[82:85]
	v_mfma_f32_16x16x32_bf16 v[110:113], v[228:231], v[172:175], v[110:113]
	v_mfma_f32_16x16x32_bf16 v[106:109], v[236:239], v[172:175], v[106:109]
	v_mfma_f32_16x16x32_bf16 v[94:97], v[228:231], v[180:183], v[94:97]
	v_mfma_f32_16x16x32_bf16 v[90:93], v[236:239], v[180:183], v[90:93]
	v_mfma_f32_16x16x32_bf16 v[78:81], v[228:231], v[188:191], v[78:81]
	v_mfma_f32_16x16x32_bf16 v[74:77], v[236:239], v[188:191], v[74:77]
	v_mfma_f32_16x16x32_bf16 v[70:73], v[228:231], v[196:199], v[70:73]
	v_mfma_f32_16x16x32_bf16 v[66:69], v[236:239], v[196:199], v[66:69]
	v_mfma_f32_16x16x32_bf16 v[110:113], v[232:235], v[176:179], v[110:113]
	v_mfma_f32_16x16x32_bf16 v[106:109], v[240:243], v[176:179], v[106:109]
	v_mfma_f32_16x16x32_bf16 v[94:97], v[232:235], v[184:187], v[94:97]
	v_mfma_f32_16x16x32_bf16 v[90:93], v[240:243], v[184:187], v[90:93]
	v_mfma_f32_16x16x32_bf16 v[78:81], v[232:235], v[192:195], v[78:81]
	v_mfma_f32_16x16x32_bf16 v[74:77], v[240:243], v[192:195], v[74:77]
	v_mfma_f32_16x16x32_bf16 v[70:73], v[232:235], v[224:227], v[70:73]
	v_mfma_f32_16x16x32_bf16 v[66:69], v[240:243], v[224:227], v[66:69]
	s_barrier
	s_mov_b32 m0, s54
	s_add_u32 s78, s50, s94
	s_addc_u32 s79, s51, s95
	ds_read_b128 v[172:175], v143 offset:16384
	ds_read_b128 v[176:179], v143 offset:17408
	ds_read_b128 v[180:183], v143 offset:18432
	ds_read_b128 v[184:187], v143 offset:19456
	ds_read_b128 v[188:191], v143 offset:20480
	ds_read_b128 v[192:195], v143 offset:21504
	ds_read_b128 v[196:199], v143 offset:22528
	ds_read_b128 v[224:227], v143 offset:23552
	global_load_lds_dwordx4 v130, s[50:51]
	s_mov_b32 m0, s55
	s_nop 0
	global_load_lds_dwordx4 v132, s[50:51]
	s_add_u32 s76, s48, s94
	s_addc_u32 s77, s49, s95
	s_mov_b32 m0, s64
	s_nop 0
	global_load_lds_dwordx4 v0, s[48:49]
	s_add_i32 m0, s64, 0x2000
	s_nop 0
	global_load_lds_dwordx4 v134, s[48:49]
	s_add_u32 s64, s48, 0x80000
	s_addc_u32 s65, s49, 0
	s_add_i32 s39, s39, s53
	s_mov_b32 m0, s39
	s_nop 0
	global_load_lds_dwordx4 v0, s[64:65]
	s_add_i32 m0, s39, 0x2000
	s_nop 0
	global_load_lds_dwordx4 v134, s[64:65]
	s_waitcnt vmcnt(6) lgkmcnt(0)
	s_barrier
	v_mfma_f32_16x16x32_bf16 v[62:65], v[144:147], v[172:175], v[62:65]
	v_mfma_f32_16x16x32_bf16 v[58:61], v[152:155], v[172:175], v[58:61]
	v_mfma_f32_16x16x32_bf16 v[54:57], v[144:147], v[180:183], v[54:57]
	v_mfma_f32_16x16x32_bf16 v[50:53], v[152:155], v[180:183], v[50:53]
	v_mfma_f32_16x16x32_bf16 v[38:41], v[144:147], v[188:191], v[38:41]
	v_mfma_f32_16x16x32_bf16 v[34:37], v[152:155], v[188:191], v[34:37]
	v_mfma_f32_16x16x32_bf16 v[22:25], v[144:147], v[196:199], v[22:25]
	v_mfma_f32_16x16x32_bf16 v[18:21], v[152:155], v[196:199], v[18:21]
	v_mfma_f32_16x16x32_bf16 v[62:65], v[148:151], v[176:179], v[62:65]
	v_mfma_f32_16x16x32_bf16 v[58:61], v[168:171], v[176:179], v[58:61]
	v_mfma_f32_16x16x32_bf16 v[54:57], v[148:151], v[184:187], v[54:57]
	v_mfma_f32_16x16x32_bf16 v[50:53], v[168:171], v[184:187], v[50:53]
	v_mfma_f32_16x16x32_bf16 v[38:41], v[148:151], v[192:195], v[38:41]
	v_mfma_f32_16x16x32_bf16 v[34:37], v[168:171], v[192:195], v[34:37]
	v_mfma_f32_16x16x32_bf16 v[22:25], v[148:151], v[224:227], v[22:25]
	v_mfma_f32_16x16x32_bf16 v[18:21], v[168:171], v[224:227], v[18:21]
	v_mfma_f32_16x16x32_bf16 v[46:49], v[228:231], v[172:175], v[46:49]
	v_mfma_f32_16x16x32_bf16 v[42:45], v[236:239], v[172:175], v[42:45]
	v_mfma_f32_16x16x32_bf16 v[30:33], v[228:231], v[180:183], v[30:33]
	v_mfma_f32_16x16x32_bf16 v[26:29], v[236:239], v[180:183], v[26:29]
	v_mfma_f32_16x16x32_bf16 v[14:17], v[228:231], v[188:191], v[14:17]
	v_mfma_f32_16x16x32_bf16 v[10:13], v[236:239], v[188:191], v[10:13]
	v_mfma_f32_16x16x32_bf16 v[6:9], v[228:231], v[196:199], v[6:9]
	v_mfma_f32_16x16x32_bf16 v[2:5], v[236:239], v[196:199], v[2:5]
	v_mfma_f32_16x16x32_bf16 v[46:49], v[232:235], v[176:179], v[46:49]
	v_mfma_f32_16x16x32_bf16 v[42:45], v[240:243], v[176:179], v[42:45]
	v_mfma_f32_16x16x32_bf16 v[30:33], v[232:235], v[184:187], v[30:33]
	v_mfma_f32_16x16x32_bf16 v[26:29], v[240:243], v[184:187], v[26:29]
	v_mfma_f32_16x16x32_bf16 v[14:17], v[232:235], v[192:195], v[14:17]
	v_mfma_f32_16x16x32_bf16 v[10:13], v[240:243], v[192:195], v[10:13]
	v_mfma_f32_16x16x32_bf16 v[6:9], v[232:235], v[224:227], v[6:9]
	v_mfma_f32_16x16x32_bf16 v[2:5], v[240:243], v[224:227], v[2:5]
	s_barrier
	s_add_i32 s39, 0, 0x18000
	ds_read_b128 v[144:147], v141 offset:32768
	ds_read_b128 v[148:151], v141 offset:33792
	ds_read_b128 v[152:155], v141 offset:34816
	ds_read_b128 v[168:171], v141 offset:35840
	s_add_u32 s50, s50, 0x80000
	s_addc_u32 s51, s51, 0
	ds_read_b128 v[172:175], v143 offset:32768
	ds_read_b128 v[176:179], v143 offset:33792
	ds_read_b128 v[180:183], v143 offset:34816
	ds_read_b128 v[184:187], v143 offset:35840
	ds_read_b128 v[188:191], v143 offset:36864
	ds_read_b128 v[192:195], v143 offset:37888
	ds_read_b128 v[196:199], v143 offset:38912
	ds_read_b128 v[224:227], v143 offset:39936
	s_mov_b32 m0, s56
	s_nop 0
	global_load_lds_dwordx4 v130, s[50:51]
	s_mov_b32 m0, s57
	s_nop 0
	global_load_lds_dwordx4 v132, s[50:51]
	s_add_i32 s50, 0, 0x1c000
	s_add_i32 s39, s39, s53
	ds_read_b128 v[228:231], v141 offset:49152
	ds_read_b128 v[232:235], v141 offset:50176
	ds_read_b128 v[236:239], v141 offset:51200
	ds_read_b128 v[240:243], v141 offset:52224
	s_waitcnt lgkmcnt(0)
	s_barrier
	v_mfma_f32_16x16x32_bf16 v[126:129], v[144:147], v[172:175], v[126:129]
	v_mfma_f32_16x16x32_bf16 v[122:125], v[152:155], v[172:175], v[122:125]
	v_mfma_f32_16x16x32_bf16 v[118:121], v[144:147], v[180:183], v[118:121]
	v_mfma_f32_16x16x32_bf16 v[114:117], v[152:155], v[180:183], v[114:117]
	v_mfma_f32_16x16x32_bf16 v[102:105], v[144:147], v[188:191], v[102:105]
	v_mfma_f32_16x16x32_bf16 v[98:101], v[152:155], v[188:191], v[98:101]
	v_mfma_f32_16x16x32_bf16 v[86:89], v[144:147], v[196:199], v[86:89]
	v_mfma_f32_16x16x32_bf16 v[82:85], v[152:155], v[196:199], v[82:85]
	v_mfma_f32_16x16x32_bf16 v[126:129], v[148:151], v[176:179], v[126:129]
	v_mfma_f32_16x16x32_bf16 v[122:125], v[168:171], v[176:179], v[122:125]
	v_mfma_f32_16x16x32_bf16 v[118:121], v[148:151], v[184:187], v[118:121]
	v_mfma_f32_16x16x32_bf16 v[114:117], v[168:171], v[184:187], v[114:117]
	v_mfma_f32_16x16x32_bf16 v[102:105], v[148:151], v[192:195], v[102:105]
	v_mfma_f32_16x16x32_bf16 v[98:101], v[168:171], v[192:195], v[98:101]
	v_mfma_f32_16x16x32_bf16 v[86:89], v[148:151], v[224:227], v[86:89]
	v_mfma_f32_16x16x32_bf16 v[82:85], v[168:171], v[224:227], v[82:85]
	v_mfma_f32_16x16x32_bf16 v[110:113], v[228:231], v[172:175], v[110:113]
	v_mfma_f32_16x16x32_bf16 v[106:109], v[236:239], v[172:175], v[106:109]
	v_mfma_f32_16x16x32_bf16 v[94:97], v[228:231], v[180:183], v[94:97]
	v_mfma_f32_16x16x32_bf16 v[90:93], v[236:239], v[180:183], v[90:93]
	v_mfma_f32_16x16x32_bf16 v[78:81], v[228:231], v[188:191], v[78:81]
	v_mfma_f32_16x16x32_bf16 v[74:77], v[236:239], v[188:191], v[74:77]
	v_mfma_f32_16x16x32_bf16 v[70:73], v[228:231], v[196:199], v[70:73]
	v_mfma_f32_16x16x32_bf16 v[66:69], v[236:239], v[196:199], v[66:69]
	v_mfma_f32_16x16x32_bf16 v[110:113], v[232:235], v[176:179], v[110:113]
	v_mfma_f32_16x16x32_bf16 v[106:109], v[240:243], v[176:179], v[106:109]
	v_mfma_f32_16x16x32_bf16 v[94:97], v[232:235], v[184:187], v[94:97]
	v_mfma_f32_16x16x32_bf16 v[90:93], v[240:243], v[184:187], v[90:93]
	v_mfma_f32_16x16x32_bf16 v[78:81], v[232:235], v[192:195], v[78:81]
	v_mfma_f32_16x16x32_bf16 v[74:77], v[240:243], v[192:195], v[74:77]
	v_mfma_f32_16x16x32_bf16 v[70:73], v[232:235], v[224:227], v[70:73]
	v_mfma_f32_16x16x32_bf16 v[66:69], v[240:243], v[224:227], v[66:69]
	s_barrier
	s_mov_b32 m0, s59
	ds_read_b128 v[172:175], v143 offset:49152
	ds_read_b128 v[176:179], v143 offset:50176
	ds_read_b128 v[180:183], v143 offset:51200
	ds_read_b128 v[184:187], v143 offset:52224
	ds_read_b128 v[188:191], v143 offset:53248
	ds_read_b128 v[192:195], v143 offset:54272
	ds_read_b128 v[196:199], v143 offset:55296
	ds_read_b128 v[224:227], v143 offset:56320
	global_load_lds_dwordx4 v130, s[78:79]
	s_mov_b32 m0, s61
	s_nop 0
	global_load_lds_dwordx4 v132, s[78:79]
	s_mov_b32 m0, s39
	s_nop 0
	global_load_lds_dwordx4 v0, s[76:77]
	s_add_i32 m0, s39, 0x2000
	s_nop 0
	global_load_lds_dwordx4 v134, s[76:77]
	s_add_u32 s48, s48, 0x80080
	s_addc_u32 s49, s49, 0
	s_add_i32 s39, s50, s53
	s_mov_b32 m0, s39
	s_nop 0
	global_load_lds_dwordx4 v0, s[48:49]
	s_add_i32 m0, s39, 0x2000
	s_nop 0
	global_load_lds_dwordx4 v134, s[48:49]
	s_waitcnt vmcnt(6) lgkmcnt(0)
	s_barrier
	v_mfma_f32_16x16x32_bf16 v[62:65], v[144:147], v[172:175], v[62:65]
	v_mfma_f32_16x16x32_bf16 v[58:61], v[152:155], v[172:175], v[58:61]
	v_mfma_f32_16x16x32_bf16 v[54:57], v[144:147], v[180:183], v[54:57]
	v_mfma_f32_16x16x32_bf16 v[50:53], v[152:155], v[180:183], v[50:53]
	v_mfma_f32_16x16x32_bf16 v[38:41], v[144:147], v[188:191], v[38:41]
	v_mfma_f32_16x16x32_bf16 v[34:37], v[152:155], v[188:191], v[34:37]
	v_mfma_f32_16x16x32_bf16 v[22:25], v[144:147], v[196:199], v[22:25]
	v_mfma_f32_16x16x32_bf16 v[18:21], v[152:155], v[196:199], v[18:21]
	v_mfma_f32_16x16x32_bf16 v[62:65], v[148:151], v[176:179], v[62:65]
	v_mfma_f32_16x16x32_bf16 v[58:61], v[168:171], v[176:179], v[58:61]
	v_mfma_f32_16x16x32_bf16 v[54:57], v[148:151], v[184:187], v[54:57]
	v_mfma_f32_16x16x32_bf16 v[50:53], v[168:171], v[184:187], v[50:53]
	v_mfma_f32_16x16x32_bf16 v[38:41], v[148:151], v[192:195], v[38:41]
	v_mfma_f32_16x16x32_bf16 v[34:37], v[168:171], v[192:195], v[34:37]
	v_mfma_f32_16x16x32_bf16 v[22:25], v[148:151], v[224:227], v[22:25]
	v_mfma_f32_16x16x32_bf16 v[18:21], v[168:171], v[224:227], v[18:21]
	v_mfma_f32_16x16x32_bf16 v[46:49], v[228:231], v[172:175], v[46:49]
	v_mfma_f32_16x16x32_bf16 v[42:45], v[236:239], v[172:175], v[42:45]
	v_mfma_f32_16x16x32_bf16 v[30:33], v[228:231], v[180:183], v[30:33]
	v_mfma_f32_16x16x32_bf16 v[26:29], v[236:239], v[180:183], v[26:29]
	v_mfma_f32_16x16x32_bf16 v[14:17], v[228:231], v[188:191], v[14:17]
	v_mfma_f32_16x16x32_bf16 v[10:13], v[236:239], v[188:191], v[10:13]
	v_mfma_f32_16x16x32_bf16 v[6:9], v[228:231], v[196:199], v[6:9]
	v_mfma_f32_16x16x32_bf16 v[2:5], v[236:239], v[196:199], v[2:5]
	v_mfma_f32_16x16x32_bf16 v[46:49], v[232:235], v[176:179], v[46:49]
	v_mfma_f32_16x16x32_bf16 v[42:45], v[240:243], v[176:179], v[42:45]
	v_mfma_f32_16x16x32_bf16 v[30:33], v[232:235], v[184:187], v[30:33]
	v_mfma_f32_16x16x32_bf16 v[26:29], v[240:243], v[184:187], v[26:29]
	v_mfma_f32_16x16x32_bf16 v[14:17], v[232:235], v[192:195], v[14:17]
	v_mfma_f32_16x16x32_bf16 v[10:13], v[240:243], v[192:195], v[10:13]
	v_mfma_f32_16x16x32_bf16 v[6:9], v[232:235], v[224:227], v[6:9]
	v_mfma_f32_16x16x32_bf16 v[2:5], v[240:243], v[224:227], v[2:5]
	s_barrier
	s_add_i32 s13, s13, 2
	s_add_u32 s46, s46, 0x100
	s_addc_u32 s47, s47, 0
	s_add_u32 s1, s1, 0x100
	s_addc_u32 s12, s12, 0
	s_cmp_gt_u32 s13, 29
	s_cbranch_scc0 .LBB0_788
	s_cmp_lg_u32 s62, 0
	s_cbranch_scc0 .LBB0_791
	s_lshl_b32 s1, s60, 8
	s_mov_b64 s[12:13], 0
	s_branch .LBB0_792
